# GEMM K-loops: one static priority raise for the wave half that starts one barrier later (waves 4-7), per-segment s_setprio toggles removed
# baseline (speedup 1.0000x reference)
.LBB0_345:
	s_xor_b64 s[34:35], s[0:1], -1
	s_cmp_lg_u32 s42, 0
	s_mov_b64 s[0:1], s[36:37]
	s_cselect_b64 s[36:37], -1, 0
	s_add_u32 s25, s38, 0x100
	v_mov_b32_e32 v2, 0
	s_addc_u32 s27, s39, 0
	s_mov_b32 s67, -2
	s_mov_b64 s[38:39], 0
	v_mov_b32_e32 v3, v2
	v_mov_b32_e32 v4, v2
	v_mov_b32_e32 v5, v2
	v_mov_b32_e32 v6, v2
	v_mov_b32_e32 v7, v2
	v_mov_b32_e32 v8, v2
	v_mov_b32_e32 v9, v2
	v_mov_b32_e32 v10, v2
	v_mov_b32_e32 v11, v2
	v_mov_b32_e32 v12, v2
	v_mov_b32_e32 v13, v2
	v_mov_b32_e32 v18, v2
	v_mov_b32_e32 v19, v2
	v_mov_b32_e32 v20, v2
	v_mov_b32_e32 v21, v2
	v_mov_b32_e32 v26, v2
	v_mov_b32_e32 v27, v2
	v_mov_b32_e32 v28, v2
	v_mov_b32_e32 v29, v2
	v_mov_b32_e32 v34, v2
	v_mov_b32_e32 v35, v2
	v_mov_b32_e32 v36, v2
	v_mov_b32_e32 v37, v2
	v_mov_b32_e32 v42, v2
	v_mov_b32_e32 v43, v2
	v_mov_b32_e32 v44, v2
	v_mov_b32_e32 v45, v2
	v_mov_b32_e32 v50, v2
	v_mov_b32_e32 v51, v2
	v_mov_b32_e32 v52, v2
	v_mov_b32_e32 v53, v2
	v_mov_b32_e32 v14, v2
	v_mov_b32_e32 v15, v2
	v_mov_b32_e32 v16, v2
	v_mov_b32_e32 v17, v2
	v_mov_b32_e32 v22, v2
	v_mov_b32_e32 v23, v2
	v_mov_b32_e32 v24, v2
	v_mov_b32_e32 v25, v2
	v_mov_b32_e32 v30, v2
	v_mov_b32_e32 v31, v2
	v_mov_b32_e32 v32, v2
	v_mov_b32_e32 v33, v2
	v_mov_b32_e32 v38, v2
	v_mov_b32_e32 v39, v2
	v_mov_b32_e32 v40, v2
	v_mov_b32_e32 v41, v2
	v_mov_b32_e32 v46, v2
	v_mov_b32_e32 v47, v2
	v_mov_b32_e32 v48, v2
	v_mov_b32_e32 v49, v2
	v_mov_b32_e32 v54, v2
	v_mov_b32_e32 v55, v2
	v_mov_b32_e32 v56, v2
	v_mov_b32_e32 v57, v2
	v_mov_b32_e32 v58, v2
	v_mov_b32_e32 v59, v2
	v_mov_b32_e32 v60, v2
	v_mov_b32_e32 v61, v2
	v_mov_b32_e32 v62, v2
	v_mov_b32_e32 v63, v2
	v_mov_b32_e32 v64, v2
	v_mov_b32_e32 v65, v2
	v_mov_b32_e32 v66, v2
	v_mov_b32_e32 v67, v2
	v_mov_b32_e32 v68, v2
	v_mov_b32_e32 v69, v2
	v_mov_b32_e32 v70, v2
	v_mov_b32_e32 v71, v2
	v_mov_b32_e32 v72, v2
	v_mov_b32_e32 v73, v2
	v_mov_b32_e32 v74, v2
	v_mov_b32_e32 v75, v2
	v_mov_b32_e32 v76, v2
	v_mov_b32_e32 v77, v2
	v_mov_b32_e32 v82, v2
	v_mov_b32_e32 v83, v2
	v_mov_b32_e32 v84, v2
	v_mov_b32_e32 v85, v2
	v_mov_b32_e32 v90, v2
	v_mov_b32_e32 v91, v2
	v_mov_b32_e32 v92, v2
	v_mov_b32_e32 v93, v2
	v_mov_b32_e32 v98, v2
	v_mov_b32_e32 v99, v2
	v_mov_b32_e32 v100, v2
	v_mov_b32_e32 v101, v2
	v_mov_b32_e32 v106, v2
	v_mov_b32_e32 v107, v2
	v_mov_b32_e32 v108, v2
	v_mov_b32_e32 v109, v2
	v_mov_b32_e32 v114, v2
	v_mov_b32_e32 v115, v2
	v_mov_b32_e32 v116, v2
	v_mov_b32_e32 v117, v2
	v_mov_b32_e32 v78, v2
	v_mov_b32_e32 v79, v2
	v_mov_b32_e32 v80, v2
	v_mov_b32_e32 v81, v2
	v_mov_b32_e32 v86, v2
	v_mov_b32_e32 v87, v2
	v_mov_b32_e32 v88, v2
	v_mov_b32_e32 v89, v2
	v_mov_b32_e32 v94, v2
	v_mov_b32_e32 v95, v2
	v_mov_b32_e32 v96, v2
	v_mov_b32_e32 v97, v2
	v_mov_b32_e32 v102, v2
	v_mov_b32_e32 v103, v2
	v_mov_b32_e32 v104, v2
	v_mov_b32_e32 v105, v2
	v_mov_b32_e32 v110, v2
	v_mov_b32_e32 v111, v2
	v_mov_b32_e32 v112, v2
	v_mov_b32_e32 v113, v2
	v_mov_b32_e32 v118, v2
	v_mov_b32_e32 v119, v2
	v_mov_b32_e32 v120, v2
	v_mov_b32_e32 v121, v2
	v_mov_b32_e32 v122, v2
	v_mov_b32_e32 v123, v2
	v_mov_b32_e32 v124, v2
	v_mov_b32_e32 v125, v2
	v_mov_b32_e32 v126, v2
	v_mov_b32_e32 v127, v2
	v_mov_b32_e32 v128, v2
	v_mov_b32_e32 v129, v2
	v_lshl_add_u64 v[146:147], s[30:31], 0, v[138:139]
	v_lshl_add_u64 v[148:149], s[30:31], 0, v[140:141]
	v_readfirstlane_b32 s98, v154
	s_lshr_b32 s98, s98, 8
	s_cmp_eq_u32 s98, 0
	s_cbranch_scc1 .Lgprio_0
	s_setprio 1
.Lgprio_0:
.LBB0_346:
	ds_read_b128 v[158:161], v153
	ds_read_b128 v[162:165], v153 offset:1024
	ds_read_b128 v[166:169], v153 offset:2048
	ds_read_b128 v[170:173], v153 offset:3072
	ds_read_b128 v[174:177], v155
	ds_read_b128 v[178:181], v155 offset:1024
	ds_read_b128 v[182:185], v155 offset:2048
	ds_read_b128 v[186:189], v155 offset:3072
	s_add_u32 s40, s30, s38
	s_addc_u32 s41, s31, s39
	s_add_u32 s42, s40, 0x100
	s_addc_u32 s43, s41, 0
	s_add_u32 s68, s25, s38
	s_addc_u32 s69, s27, s39
	s_cmp_eq_u32 s38, 0
	s_cselect_b64 s[40:41], -1, 0
	s_and_b64 s[40:41], s[36:37], s[40:41]
	s_cmpk_eq_i32 s38, 0xf00
	v_cndmask_b32_e64 v157, 0, 1, s[40:41]
	s_cselect_b32 s43, s7, s43
	s_cselect_b32 s42, s6, s42
	v_readfirstlane_b32 s70, v157
	s_cselect_b32 s41, s29, s69
	s_cselect_b32 s40, s28, s68
	v_lshl_add_u64 v[222:223], v[148:149], 0, s[38:39]
	s_add_i32 m0, s49, 0xc000
	ds_read_b128 v[190:193], v156
	ds_read_b128 v[194:197], v156 offset:1024
	ds_read_b128 v[198:201], v156 offset:2048
	ds_read_b128 v[202:205], v156 offset:3072
	ds_read_b128 v[206:209], v156 offset:4096
	ds_read_b128 v[210:213], v156 offset:5120
	ds_read_b128 v[214:217], v156 offset:6144
	ds_read_b128 v[218:221], v156 offset:7168
	global_load_lds_dwordx4 v[222:223], off
	v_lshl_add_u64 v[222:223], v[146:147], 0, s[38:39]
	s_add_i32 m0, s49, 0xe000
	s_and_b32 s70, s70, 1
	global_load_lds_dwordx4 v[222:223], off
	s_cmp_eq_u32 s70, 0
	s_cbranch_scc1 .Lw8_0
	s_waitcnt vmcnt(24)
	s_branch .Lwe_0

.Lwe_0:
	s_waitcnt lgkmcnt(0)
	s_barrier
	s_nop 0
	s_waitcnt lgkmcnt(0)
	v_mfma_f32_16x16x32_bf16 v[126:129], v[158:161], v[190:193], v[126:129]
	v_mfma_f32_16x16x32_bf16 v[122:125], v[166:169], v[190:193], v[122:125]
	v_mfma_f32_16x16x32_bf16 v[118:121], v[158:161], v[198:201], v[118:121]
	v_mfma_f32_16x16x32_bf16 v[110:113], v[166:169], v[198:201], v[110:113]
	v_mfma_f32_16x16x32_bf16 v[102:105], v[158:161], v[206:209], v[102:105]
	v_mfma_f32_16x16x32_bf16 v[94:97], v[166:169], v[206:209], v[94:97]
	v_mfma_f32_16x16x32_bf16 v[86:89], v[158:161], v[214:217], v[86:89]
	v_mfma_f32_16x16x32_bf16 v[78:81], v[166:169], v[214:217], v[78:81]
	v_mfma_f32_16x16x32_bf16 v[126:129], v[162:165], v[194:197], v[126:129]
	v_mfma_f32_16x16x32_bf16 v[122:125], v[170:173], v[194:197], v[122:125]
	v_mfma_f32_16x16x32_bf16 v[118:121], v[162:165], v[202:205], v[118:121]
	v_mfma_f32_16x16x32_bf16 v[110:113], v[170:173], v[202:205], v[110:113]
	v_mfma_f32_16x16x32_bf16 v[102:105], v[162:165], v[210:213], v[102:105]
	v_mfma_f32_16x16x32_bf16 v[94:97], v[170:173], v[210:213], v[94:97]
	v_mfma_f32_16x16x32_bf16 v[86:89], v[162:165], v[218:221], v[86:89]
	v_mfma_f32_16x16x32_bf16 v[78:81], v[170:173], v[218:221], v[78:81]
	s_nop 0
	s_nop 0
	v_mfma_f32_16x16x32_bf16 v[114:117], v[174:177], v[190:193], v[114:117]
	v_mfma_f32_16x16x32_bf16 v[106:109], v[182:185], v[190:193], v[106:109]
	v_mfma_f32_16x16x32_bf16 v[98:101], v[174:177], v[198:201], v[98:101]
	v_mfma_f32_16x16x32_bf16 v[90:93], v[182:185], v[198:201], v[90:93]
	v_mfma_f32_16x16x32_bf16 v[82:85], v[174:177], v[206:209], v[82:85]
	v_mfma_f32_16x16x32_bf16 v[74:77], v[182:185], v[206:209], v[74:77]
	v_mfma_f32_16x16x32_bf16 v[70:73], v[174:177], v[214:217], v[70:73]
	v_mfma_f32_16x16x32_bf16 v[66:69], v[182:185], v[214:217], v[66:69]
	v_mfma_f32_16x16x32_bf16 v[114:117], v[178:181], v[194:197], v[114:117]
	v_mfma_f32_16x16x32_bf16 v[106:109], v[186:189], v[194:197], v[106:109]
	v_mfma_f32_16x16x32_bf16 v[98:101], v[178:181], v[202:205], v[98:101]
	v_mfma_f32_16x16x32_bf16 v[90:93], v[186:189], v[202:205], v[90:93]
	v_mfma_f32_16x16x32_bf16 v[82:85], v[178:181], v[210:213], v[82:85]
	v_mfma_f32_16x16x32_bf16 v[74:77], v[186:189], v[210:213], v[74:77]
	v_mfma_f32_16x16x32_bf16 v[70:73], v[178:181], v[218:221], v[70:73]
	v_mfma_f32_16x16x32_bf16 v[66:69], v[186:189], v[218:221], v[66:69]
	s_nop 0
	s_barrier
	s_add_i32 s68, s58, s46
	v_lshl_add_u64 v[222:223], s[40:41], 0, v[134:135]
	s_mov_b32 m0, s68
	ds_read_b128 v[190:193], v156 offset:16384
	ds_read_b128 v[194:197], v156 offset:17408
	ds_read_b128 v[198:201], v156 offset:18432
	ds_read_b128 v[202:205], v156 offset:19456
	ds_read_b128 v[206:209], v156 offset:20480
	ds_read_b128 v[210:213], v156 offset:21504
	ds_read_b128 v[214:217], v156 offset:22528
	ds_read_b128 v[218:221], v156 offset:23552
	global_load_lds_dwordx4 v[222:223], off
	s_add_i32 m0, s68, 0x2000
	s_add_u32 s68, s40, 0x80000
	v_lshl_add_u64 v[224:225], s[40:41], 0, v[130:131]
	s_addc_u32 s69, s41, 0
	s_add_i32 s71, s59, s46
	global_load_lds_dwordx4 v[224:225], off
	v_lshl_add_u64 v[226:227], s[68:69], 0, v[134:135]
	s_mov_b32 m0, s71
	v_lshl_add_u64 v[228:229], s[42:43], 0, v[132:133]
	global_load_lds_dwordx4 v[226:227], off
	v_lshl_add_u64 v[226:227], s[68:69], 0, v[130:131]
	s_add_i32 m0, s71, 0x2000
	s_nop 0
	global_load_lds_dwordx4 v[226:227], off
	v_lshl_add_u64 v[226:227], s[42:43], 0, v[136:137]
	s_mov_b32 m0, s49
	s_nop 0
	global_load_lds_dwordx4 v[226:227], off
	s_mov_b32 m0, s50
	s_nop 0
	global_load_lds_dwordx4 v[228:229], off
	s_cmp_eq_u32 s70, 0
	s_cbranch_scc1 .Lw8_1
	s_waitcnt vmcnt(24)
	s_branch .Lwe_1

.Lwe_1:
	s_waitcnt lgkmcnt(0)
	s_barrier
	s_nop 0
	s_waitcnt lgkmcnt(0)
	v_mfma_f32_16x16x32_bf16 v[62:65], v[158:161], v[190:193], v[62:65]
	v_mfma_f32_16x16x32_bf16 v[58:61], v[166:169], v[190:193], v[58:61]
	v_mfma_f32_16x16x32_bf16 v[54:57], v[158:161], v[198:201], v[54:57]
	v_mfma_f32_16x16x32_bf16 v[46:49], v[166:169], v[198:201], v[46:49]
	v_mfma_f32_16x16x32_bf16 v[38:41], v[158:161], v[206:209], v[38:41]
	v_mfma_f32_16x16x32_bf16 v[30:33], v[166:169], v[206:209], v[30:33]
	v_mfma_f32_16x16x32_bf16 v[22:25], v[158:161], v[214:217], v[22:25]
	v_mfma_f32_16x16x32_bf16 v[14:17], v[166:169], v[214:217], v[14:17]
	v_mfma_f32_16x16x32_bf16 v[62:65], v[162:165], v[194:197], v[62:65]
	v_mfma_f32_16x16x32_bf16 v[58:61], v[170:173], v[194:197], v[58:61]
	v_mfma_f32_16x16x32_bf16 v[54:57], v[162:165], v[202:205], v[54:57]
	v_mfma_f32_16x16x32_bf16 v[46:49], v[170:173], v[202:205], v[46:49]
	v_mfma_f32_16x16x32_bf16 v[38:41], v[162:165], v[210:213], v[38:41]
	v_mfma_f32_16x16x32_bf16 v[30:33], v[170:173], v[210:213], v[30:33]
	v_mfma_f32_16x16x32_bf16 v[22:25], v[162:165], v[218:221], v[22:25]
	v_mfma_f32_16x16x32_bf16 v[14:17], v[170:173], v[218:221], v[14:17]
	s_nop 0
	s_nop 0
	v_mfma_f32_16x16x32_bf16 v[50:53], v[174:177], v[190:193], v[50:53]
	v_mfma_f32_16x16x32_bf16 v[42:45], v[182:185], v[190:193], v[42:45]
	v_mfma_f32_16x16x32_bf16 v[34:37], v[174:177], v[198:201], v[34:37]
	v_mfma_f32_16x16x32_bf16 v[26:29], v[182:185], v[198:201], v[26:29]
	v_mfma_f32_16x16x32_bf16 v[18:21], v[174:177], v[206:209], v[18:21]
	v_mfma_f32_16x16x32_bf16 v[10:13], v[182:185], v[206:209], v[10:13]
	v_mfma_f32_16x16x32_bf16 v[6:9], v[174:177], v[214:217], v[6:9]
	v_mfma_f32_16x16x32_bf16 v[2:5], v[182:185], v[214:217], v[2:5]
	v_mfma_f32_16x16x32_bf16 v[50:53], v[178:181], v[194:197], v[50:53]
	v_mfma_f32_16x16x32_bf16 v[42:45], v[186:189], v[194:197], v[42:45]
	v_mfma_f32_16x16x32_bf16 v[34:37], v[178:181], v[202:205], v[34:37]
	v_mfma_f32_16x16x32_bf16 v[26:29], v[186:189], v[202:205], v[26:29]
	v_mfma_f32_16x16x32_bf16 v[18:21], v[178:181], v[210:213], v[18:21]
	v_mfma_f32_16x16x32_bf16 v[10:13], v[186:189], v[210:213], v[10:13]
	v_mfma_f32_16x16x32_bf16 v[6:9], v[178:181], v[218:221], v[6:9]
	v_mfma_f32_16x16x32_bf16 v[2:5], v[186:189], v[218:221], v[2:5]
	s_nop 0
	s_barrier
	s_add_i32 s68, 0, 0x18000
	v_add_u32_e32 v157, s68, v150
	s_add_i32 s69, 0, 0x1c000
	ds_read_b128 v[158:161], v157
	ds_read_b128 v[162:165], v157 offset:1024
	ds_read_b128 v[166:169], v157 offset:2048
	ds_read_b128 v[170:173], v157 offset:3072
	v_add_u32_e32 v157, s69, v150
	ds_read_b128 v[174:177], v157
	ds_read_b128 v[178:181], v157 offset:1024
	ds_read_b128 v[182:185], v157 offset:2048
	ds_read_b128 v[186:189], v157 offset:3072
	s_add_u32 s42, s42, 0x80000
	s_addc_u32 s43, s43, 0
	s_mov_b32 m0, s51
	v_lshl_add_u64 v[230:231], s[42:43], 0, v[136:137]
	ds_read_b128 v[190:193], v156 offset:32768
	ds_read_b128 v[194:197], v156 offset:33792
	ds_read_b128 v[198:201], v156 offset:34816
	ds_read_b128 v[202:205], v156 offset:35840
	ds_read_b128 v[206:209], v156 offset:36864
	ds_read_b128 v[210:213], v156 offset:37888
	ds_read_b128 v[214:217], v156 offset:38912
	ds_read_b128 v[218:221], v156 offset:39936
	global_load_lds_dwordx4 v[230:231], off
	v_lshl_add_u64 v[230:231], s[42:43], 0, v[132:133]
	s_mov_b32 m0, s52
	s_nop 0
	global_load_lds_dwordx4 v[230:231], off
	s_waitcnt vmcnt(8)
	s_waitcnt lgkmcnt(0)
	s_barrier
	s_nop 0
	s_waitcnt lgkmcnt(0)
	v_mfma_f32_16x16x32_bf16 v[126:129], v[158:161], v[190:193], v[126:129]
	v_mfma_f32_16x16x32_bf16 v[122:125], v[166:169], v[190:193], v[122:125]
	v_mfma_f32_16x16x32_bf16 v[118:121], v[158:161], v[198:201], v[118:121]
	v_mfma_f32_16x16x32_bf16 v[110:113], v[166:169], v[198:201], v[110:113]
	v_mfma_f32_16x16x32_bf16 v[102:105], v[158:161], v[206:209], v[102:105]
	v_mfma_f32_16x16x32_bf16 v[94:97], v[166:169], v[206:209], v[94:97]
	v_mfma_f32_16x16x32_bf16 v[86:89], v[158:161], v[214:217], v[86:89]
	v_mfma_f32_16x16x32_bf16 v[78:81], v[166:169], v[214:217], v[78:81]
	v_mfma_f32_16x16x32_bf16 v[126:129], v[162:165], v[194:197], v[126:129]
	v_mfma_f32_16x16x32_bf16 v[122:125], v[170:173], v[194:197], v[122:125]
	v_mfma_f32_16x16x32_bf16 v[118:121], v[162:165], v[202:205], v[118:121]
	v_mfma_f32_16x16x32_bf16 v[110:113], v[170:173], v[202:205], v[110:113]
	v_mfma_f32_16x16x32_bf16 v[102:105], v[162:165], v[210:213], v[102:105]
	v_mfma_f32_16x16x32_bf16 v[94:97], v[170:173], v[210:213], v[94:97]
	v_mfma_f32_16x16x32_bf16 v[86:89], v[162:165], v[218:221], v[86:89]
	v_mfma_f32_16x16x32_bf16 v[78:81], v[170:173], v[218:221], v[78:81]
	s_nop 0
	s_nop 0
	v_mfma_f32_16x16x32_bf16 v[114:117], v[174:177], v[190:193], v[114:117]
	v_mfma_f32_16x16x32_bf16 v[106:109], v[182:185], v[190:193], v[106:109]
	v_mfma_f32_16x16x32_bf16 v[98:101], v[174:177], v[198:201], v[98:101]
	v_mfma_f32_16x16x32_bf16 v[90:93], v[182:185], v[198:201], v[90:93]
	v_mfma_f32_16x16x32_bf16 v[82:85], v[174:177], v[206:209], v[82:85]
	v_mfma_f32_16x16x32_bf16 v[74:77], v[182:185], v[206:209], v[74:77]
	v_mfma_f32_16x16x32_bf16 v[70:73], v[174:177], v[214:217], v[70:73]
	v_mfma_f32_16x16x32_bf16 v[66:69], v[182:185], v[214:217], v[66:69]
	v_mfma_f32_16x16x32_bf16 v[114:117], v[178:181], v[194:197], v[114:117]
	v_mfma_f32_16x16x32_bf16 v[106:109], v[186:189], v[194:197], v[106:109]
	v_mfma_f32_16x16x32_bf16 v[98:101], v[178:181], v[202:205], v[98:101]
	v_mfma_f32_16x16x32_bf16 v[90:93], v[186:189], v[202:205], v[90:93]
	v_mfma_f32_16x16x32_bf16 v[82:85], v[178:181], v[210:213], v[82:85]
	v_mfma_f32_16x16x32_bf16 v[74:77], v[186:189], v[210:213], v[74:77]
	v_mfma_f32_16x16x32_bf16 v[70:73], v[178:181], v[218:221], v[70:73]
	v_mfma_f32_16x16x32_bf16 v[66:69], v[186:189], v[218:221], v[66:69]
	s_nop 0
	s_barrier
	s_add_i32 s42, s68, s46
	v_lshl_add_u64 v[222:223], v[222:223], 0, s[12:13]
	s_mov_b32 m0, s42
	ds_read_b128 v[190:193], v156 offset:49152
	ds_read_b128 v[194:197], v156 offset:50176
	ds_read_b128 v[198:201], v156 offset:51200
	ds_read_b128 v[202:205], v156 offset:52224
	ds_read_b128 v[206:209], v156 offset:53248
	ds_read_b128 v[210:213], v156 offset:54272
	ds_read_b128 v[214:217], v156 offset:55296
	ds_read_b128 v[218:221], v156 offset:56320
	global_load_lds_dwordx4 v[222:223], off
	s_add_i32 m0, s42, 0x2000
	s_add_u32 s40, s40, 0x80080
	v_lshl_add_u64 v[222:223], v[224:225], 0, s[12:13]
	s_addc_u32 s41, s41, 0
	s_add_i32 s42, s69, s46
	global_load_lds_dwordx4 v[222:223], off
	v_lshl_add_u64 v[222:223], s[40:41], 0, v[134:135]
	s_mov_b32 m0, s42
	s_nop 0
	global_load_lds_dwordx4 v[222:223], off
	v_lshl_add_u64 v[222:223], s[40:41], 0, v[130:131]
	s_add_i32 m0, s42, 0x2000
	s_nop 0
	global_load_lds_dwordx4 v[222:223], off
	v_lshl_add_u64 v[222:223], v[226:227], 0, s[12:13]
	s_mov_b32 m0, s54
	s_nop 0
	global_load_lds_dwordx4 v[222:223], off
	v_lshl_add_u64 v[222:223], v[228:229], 0, s[12:13]
	s_mov_b32 m0, s55
	s_nop 0
	global_load_lds_dwordx4 v[222:223], off
	s_waitcnt vmcnt(8)
	s_waitcnt lgkmcnt(0)
	s_barrier
	s_nop 0
	s_waitcnt lgkmcnt(0)
	v_mfma_f32_16x16x32_bf16 v[62:65], v[158:161], v[190:193], v[62:65]
	v_mfma_f32_16x16x32_bf16 v[58:61], v[166:169], v[190:193], v[58:61]
	v_mfma_f32_16x16x32_bf16 v[54:57], v[158:161], v[198:201], v[54:57]
	v_mfma_f32_16x16x32_bf16 v[46:49], v[166:169], v[198:201], v[46:49]
	v_mfma_f32_16x16x32_bf16 v[38:41], v[158:161], v[206:209], v[38:41]
	v_mfma_f32_16x16x32_bf16 v[30:33], v[166:169], v[206:209], v[30:33]
	v_mfma_f32_16x16x32_bf16 v[22:25], v[158:161], v[214:217], v[22:25]
	v_mfma_f32_16x16x32_bf16 v[14:17], v[166:169], v[214:217], v[14:17]
	v_mfma_f32_16x16x32_bf16 v[62:65], v[162:165], v[194:197], v[62:65]
	v_mfma_f32_16x16x32_bf16 v[58:61], v[170:173], v[194:197], v[58:61]
	v_mfma_f32_16x16x32_bf16 v[54:57], v[162:165], v[202:205], v[54:57]
	v_mfma_f32_16x16x32_bf16 v[46:49], v[170:173], v[202:205], v[46:49]
	v_mfma_f32_16x16x32_bf16 v[38:41], v[162:165], v[210:213], v[38:41]
	v_mfma_f32_16x16x32_bf16 v[30:33], v[170:173], v[210:213], v[30:33]
	v_mfma_f32_16x16x32_bf16 v[22:25], v[162:165], v[218:221], v[22:25]
	v_mfma_f32_16x16x32_bf16 v[14:17], v[170:173], v[218:221], v[14:17]
	s_nop 0
	s_nop 0
	v_mfma_f32_16x16x32_bf16 v[50:53], v[174:177], v[190:193], v[50:53]
	v_mfma_f32_16x16x32_bf16 v[42:45], v[182:185], v[190:193], v[42:45]
	v_mfma_f32_16x16x32_bf16 v[34:37], v[174:177], v[198:201], v[34:37]
	v_mfma_f32_16x16x32_bf16 v[26:29], v[182:185], v[198:201], v[26:29]
	v_mfma_f32_16x16x32_bf16 v[18:21], v[174:177], v[206:209], v[18:21]
	v_mfma_f32_16x16x32_bf16 v[10:13], v[182:185], v[206:209], v[10:13]
	v_mfma_f32_16x16x32_bf16 v[6:9], v[174:177], v[214:217], v[6:9]
	v_mfma_f32_16x16x32_bf16 v[2:5], v[182:185], v[214:217], v[2:5]
	v_mfma_f32_16x16x32_bf16 v[50:53], v[178:181], v[194:197], v[50:53]
	v_mfma_f32_16x16x32_bf16 v[42:45], v[186:189], v[194:197], v[42:45]
	v_mfma_f32_16x16x32_bf16 v[34:37], v[178:181], v[202:205], v[34:37]
	v_mfma_f32_16x16x32_bf16 v[26:29], v[186:189], v[202:205], v[26:29]
	v_mfma_f32_16x16x32_bf16 v[18:21], v[178:181], v[210:213], v[18:21]
	v_mfma_f32_16x16x32_bf16 v[10:13], v[186:189], v[210:213], v[10:13]
	v_mfma_f32_16x16x32_bf16 v[6:9], v[178:181], v[218:221], v[6:9]
	v_mfma_f32_16x16x32_bf16 v[2:5], v[186:189], v[218:221], v[2:5]
	s_nop 0
	s_barrier
	s_add_i32 s67, s67, 2
	s_add_u32 s38, s38, 0x100
	s_addc_u32 s39, s39, 0
	s_cmp_gt_u32 s67, 29
	s_cbranch_scc0 .LBB0_346
	s_setprio 0
	s_and_b64 vcc, exec, s[14:15]
	s_cbranch_vccnz .LBB0_351
	s_mov_b64 s[30:31], -1
	s_and_b64 vcc, exec, s[34:35]
	s_cbranch_vccnz .LBB0_352

.LBB0_890:
	s_ashr_i32 s17, s16, 31
	s_lshl_b64 s[18:19], s[16:17], 19
	s_add_u32 s18, s37, s18
	s_addc_u32 s19, s38, s19
	s_and_b64 s[20:21], s[4:5], exec
	s_cselect_b32 s17, s19, s25
	s_cselect_b32 s54, s18, s24
	s_ashr_i32 s15, s14, 31
	s_lshl_b64 s[20:21], s[14:15], 19
	s_add_u32 s20, s39, s20
	s_addc_u32 s21, s40, s21
	s_and_b64 s[30:31], s[4:5], exec
	s_cselect_b32 s15, s21, s29
	s_cselect_b32 s55, s20, s28
	s_cmp_lg_u32 s26, 0
	s_cselect_b64 s[26:27], -1, 0
	s_add_u32 s56, s28, 0x100
	v_mov_b32_e32 v2, 0
	s_addc_u32 s57, s29, 0
	v_lshl_add_u64 v[146:147], s[24:25], 0, v[138:139]
	v_lshl_add_u64 v[148:149], s[24:25], 0, v[140:141]
	s_mov_b32 s58, -2
	s_mov_b64 s[28:29], 0
	v_mov_b32_e32 v3, v2
	v_mov_b32_e32 v4, v2
	v_mov_b32_e32 v5, v2
	v_mov_b32_e32 v6, v2
	v_mov_b32_e32 v7, v2
	v_mov_b32_e32 v8, v2
	v_mov_b32_e32 v9, v2
	v_mov_b32_e32 v18, v2
	v_mov_b32_e32 v19, v2
	v_mov_b32_e32 v20, v2
	v_mov_b32_e32 v21, v2
	v_mov_b32_e32 v22, v2
	v_mov_b32_e32 v23, v2
	v_mov_b32_e32 v24, v2
	v_mov_b32_e32 v25, v2
	v_mov_b32_e32 v34, v2
	v_mov_b32_e32 v35, v2
	v_mov_b32_e32 v36, v2
	v_mov_b32_e32 v37, v2
	v_mov_b32_e32 v38, v2
	v_mov_b32_e32 v39, v2
	v_mov_b32_e32 v40, v2
	v_mov_b32_e32 v41, v2
	v_mov_b32_e32 v50, v2
	v_mov_b32_e32 v51, v2
	v_mov_b32_e32 v52, v2
	v_mov_b32_e32 v53, v2
	v_mov_b32_e32 v54, v2
	v_mov_b32_e32 v55, v2
	v_mov_b32_e32 v56, v2
	v_mov_b32_e32 v57, v2
	v_mov_b32_e32 v10, v2
	v_mov_b32_e32 v11, v2
	v_mov_b32_e32 v12, v2
	v_mov_b32_e32 v13, v2
	v_mov_b32_e32 v14, v2
	v_mov_b32_e32 v15, v2
	v_mov_b32_e32 v16, v2
	v_mov_b32_e32 v17, v2
	v_mov_b32_e32 v26, v2
	v_mov_b32_e32 v27, v2
	v_mov_b32_e32 v28, v2
	v_mov_b32_e32 v29, v2
	v_mov_b32_e32 v30, v2
	v_mov_b32_e32 v31, v2
	v_mov_b32_e32 v32, v2
	v_mov_b32_e32 v33, v2
	v_mov_b32_e32 v42, v2
	v_mov_b32_e32 v43, v2
	v_mov_b32_e32 v44, v2
	v_mov_b32_e32 v45, v2
	v_mov_b32_e32 v46, v2
	v_mov_b32_e32 v47, v2
	v_mov_b32_e32 v48, v2
	v_mov_b32_e32 v49, v2
	v_mov_b32_e32 v58, v2
	v_mov_b32_e32 v59, v2
	v_mov_b32_e32 v60, v2
	v_mov_b32_e32 v61, v2
	v_mov_b32_e32 v62, v2
	v_mov_b32_e32 v63, v2
	v_mov_b32_e32 v64, v2
	v_mov_b32_e32 v65, v2
	v_mov_b32_e32 v66, v2
	v_mov_b32_e32 v67, v2
	v_mov_b32_e32 v68, v2
	v_mov_b32_e32 v69, v2
	v_mov_b32_e32 v70, v2
	v_mov_b32_e32 v71, v2
	v_mov_b32_e32 v72, v2
	v_mov_b32_e32 v73, v2
	v_mov_b32_e32 v82, v2
	v_mov_b32_e32 v83, v2
	v_mov_b32_e32 v84, v2
	v_mov_b32_e32 v85, v2
	v_mov_b32_e32 v86, v2
	v_mov_b32_e32 v87, v2
	v_mov_b32_e32 v88, v2
	v_mov_b32_e32 v89, v2
	v_mov_b32_e32 v98, v2
	v_mov_b32_e32 v99, v2
	v_mov_b32_e32 v100, v2
	v_mov_b32_e32 v101, v2
	v_mov_b32_e32 v102, v2
	v_mov_b32_e32 v103, v2
	v_mov_b32_e32 v104, v2
	v_mov_b32_e32 v105, v2
	v_mov_b32_e32 v114, v2
	v_mov_b32_e32 v115, v2
	v_mov_b32_e32 v116, v2
	v_mov_b32_e32 v117, v2
	v_mov_b32_e32 v118, v2
	v_mov_b32_e32 v119, v2
	v_mov_b32_e32 v120, v2
	v_mov_b32_e32 v121, v2
	v_mov_b32_e32 v74, v2
	v_mov_b32_e32 v75, v2
	v_mov_b32_e32 v76, v2
	v_mov_b32_e32 v77, v2
	v_mov_b32_e32 v78, v2
	v_mov_b32_e32 v79, v2
	v_mov_b32_e32 v80, v2
	v_mov_b32_e32 v81, v2
	v_mov_b32_e32 v90, v2
	v_mov_b32_e32 v91, v2
	v_mov_b32_e32 v92, v2
	v_mov_b32_e32 v93, v2
	v_mov_b32_e32 v94, v2
	v_mov_b32_e32 v95, v2
	v_mov_b32_e32 v96, v2
	v_mov_b32_e32 v97, v2
	v_mov_b32_e32 v106, v2
	v_mov_b32_e32 v107, v2
	v_mov_b32_e32 v108, v2
	v_mov_b32_e32 v109, v2
	v_mov_b32_e32 v110, v2
	v_mov_b32_e32 v111, v2
	v_mov_b32_e32 v112, v2
	v_mov_b32_e32 v113, v2
	v_mov_b32_e32 v122, v2
	v_mov_b32_e32 v123, v2
	v_mov_b32_e32 v124, v2
	v_mov_b32_e32 v125, v2
	v_mov_b32_e32 v126, v2
	v_mov_b32_e32 v127, v2
	v_mov_b32_e32 v128, v2
	v_mov_b32_e32 v129, v2
	v_readfirstlane_b32 s98, v154
	s_lshr_b32 s98, s98, 8
	s_cmp_eq_u32 s98, 0
	s_cbranch_scc1 .Lgprio_1
	s_setprio 1
.Lgprio_1:
.LBB0_891:
	ds_read_b128 v[158:161], v155
	ds_read_b128 v[162:165], v155 offset:1024
	ds_read_b128 v[166:169], v155 offset:2048
	ds_read_b128 v[170:173], v155 offset:3072
	ds_read_b128 v[174:177], v156
	ds_read_b128 v[178:181], v156 offset:1024
	ds_read_b128 v[182:185], v156 offset:2048
	ds_read_b128 v[186:189], v156 offset:3072
	s_add_u32 s30, s24, s28
	s_addc_u32 s31, s25, s29
	s_add_u32 s34, s30, 0x100
	s_addc_u32 s35, s31, 0
	s_add_u32 s59, s56, s28
	s_addc_u32 s60, s57, s29
	s_cmp_eq_u32 s28, 0
	s_cselect_b64 s[30:31], -1, 0
	s_and_b64 s[30:31], s[26:27], s[30:31]
	s_cmpk_eq_i32 s28, 0x700
	v_cndmask_b32_e64 v150, 0, 1, s[30:31]
	s_cselect_b32 s35, s17, s35
	s_cselect_b32 s34, s54, s34
	v_readfirstlane_b32 s61, v150
	s_cselect_b32 s31, s15, s60
	s_cselect_b32 s30, s55, s59
	v_lshl_add_u64 v[150:151], v[148:149], 0, s[28:29]
	s_add_i32 m0, s23, 0xc000
	ds_read_b128 v[190:193], v157
	ds_read_b128 v[194:197], v157 offset:1024
	ds_read_b128 v[198:201], v157 offset:2048
	ds_read_b128 v[202:205], v157 offset:3072
	ds_read_b128 v[206:209], v157 offset:4096
	ds_read_b128 v[210:213], v157 offset:5120
	ds_read_b128 v[214:217], v157 offset:6144
	ds_read_b128 v[218:221], v157 offset:7168
	global_load_lds_dwordx4 v[150:151], off
	v_lshl_add_u64 v[150:151], v[146:147], 0, s[28:29]
	s_add_i32 m0, s23, 0xe000
	s_and_b32 s59, s61, 1
	global_load_lds_dwordx4 v[150:151], off
	s_cmp_eq_u32 s59, 0
	s_cbranch_scc1 .Lw8_2
	s_waitcnt vmcnt(24)
	s_branch .Lwe_2

.Lwe_2:
	s_waitcnt lgkmcnt(0)
	s_barrier
	s_nop 0
	s_waitcnt lgkmcnt(0)
	v_mfma_f32_16x16x32_bf16 v[126:129], v[158:161], v[190:193], v[126:129]
	v_mfma_f32_16x16x32_bf16 v[122:125], v[166:169], v[190:193], v[122:125]
	v_mfma_f32_16x16x32_bf16 v[110:113], v[158:161], v[198:201], v[110:113]
	v_mfma_f32_16x16x32_bf16 v[106:109], v[166:169], v[198:201], v[106:109]
	v_mfma_f32_16x16x32_bf16 v[94:97], v[158:161], v[206:209], v[94:97]
	v_mfma_f32_16x16x32_bf16 v[90:93], v[166:169], v[206:209], v[90:93]
	v_mfma_f32_16x16x32_bf16 v[78:81], v[158:161], v[214:217], v[78:81]
	v_mfma_f32_16x16x32_bf16 v[74:77], v[166:169], v[214:217], v[74:77]
	v_mfma_f32_16x16x32_bf16 v[126:129], v[162:165], v[194:197], v[126:129]
	v_mfma_f32_16x16x32_bf16 v[122:125], v[170:173], v[194:197], v[122:125]
	v_mfma_f32_16x16x32_bf16 v[110:113], v[162:165], v[202:205], v[110:113]
	v_mfma_f32_16x16x32_bf16 v[106:109], v[170:173], v[202:205], v[106:109]
	v_mfma_f32_16x16x32_bf16 v[94:97], v[162:165], v[210:213], v[94:97]
	v_mfma_f32_16x16x32_bf16 v[90:93], v[170:173], v[210:213], v[90:93]
	v_mfma_f32_16x16x32_bf16 v[78:81], v[162:165], v[218:221], v[78:81]
	v_mfma_f32_16x16x32_bf16 v[74:77], v[170:173], v[218:221], v[74:77]
	s_nop 0
	s_nop 0
	v_mfma_f32_16x16x32_bf16 v[118:121], v[174:177], v[190:193], v[118:121]
	v_mfma_f32_16x16x32_bf16 v[114:117], v[182:185], v[190:193], v[114:117]
	v_mfma_f32_16x16x32_bf16 v[102:105], v[174:177], v[198:201], v[102:105]
	v_mfma_f32_16x16x32_bf16 v[98:101], v[182:185], v[198:201], v[98:101]
	v_mfma_f32_16x16x32_bf16 v[86:89], v[174:177], v[206:209], v[86:89]
	v_mfma_f32_16x16x32_bf16 v[82:85], v[182:185], v[206:209], v[82:85]
	v_mfma_f32_16x16x32_bf16 v[70:73], v[174:177], v[214:217], v[70:73]
	v_mfma_f32_16x16x32_bf16 v[66:69], v[182:185], v[214:217], v[66:69]
	v_mfma_f32_16x16x32_bf16 v[118:121], v[178:181], v[194:197], v[118:121]
	v_mfma_f32_16x16x32_bf16 v[114:117], v[186:189], v[194:197], v[114:117]
	v_mfma_f32_16x16x32_bf16 v[102:105], v[178:181], v[202:205], v[102:105]
	v_mfma_f32_16x16x32_bf16 v[98:101], v[186:189], v[202:205], v[98:101]
	v_mfma_f32_16x16x32_bf16 v[86:89], v[178:181], v[210:213], v[86:89]
	v_mfma_f32_16x16x32_bf16 v[82:85], v[186:189], v[210:213], v[82:85]
	v_mfma_f32_16x16x32_bf16 v[70:73], v[178:181], v[218:221], v[70:73]
	v_mfma_f32_16x16x32_bf16 v[66:69], v[186:189], v[218:221], v[66:69]
	s_nop 0
	s_barrier
	s_add_i32 s60, s50, s41
	v_lshl_add_u64 v[150:151], s[30:31], 0, v[132:133]
	s_mov_b32 m0, s60
	ds_read_b128 v[190:193], v157 offset:16384
	ds_read_b128 v[194:197], v157 offset:17408
	ds_read_b128 v[198:201], v157 offset:18432
	ds_read_b128 v[202:205], v157 offset:19456
	ds_read_b128 v[206:209], v157 offset:20480
	ds_read_b128 v[210:213], v157 offset:21504
	ds_read_b128 v[214:217], v157 offset:22528
	ds_read_b128 v[218:221], v157 offset:23552
	global_load_lds_dwordx4 v[150:151], off
	s_add_i32 m0, s60, 0x2000
	s_add_u32 s60, s30, 0x40000
	v_lshl_add_u64 v[222:223], s[30:31], 0, v[136:137]
	s_addc_u32 s61, s31, 0
	s_add_i32 s62, s51, s41
	global_load_lds_dwordx4 v[222:223], off
	v_lshl_add_u64 v[224:225], s[60:61], 0, v[132:133]
	s_mov_b32 m0, s62
	v_lshl_add_u64 v[226:227], s[34:35], 0, v[134:135]
	global_load_lds_dwordx4 v[224:225], off
	v_lshl_add_u64 v[224:225], s[60:61], 0, v[136:137]
	s_add_i32 m0, s62, 0x2000
	s_nop 0
	global_load_lds_dwordx4 v[224:225], off
	v_lshl_add_u64 v[224:225], s[34:35], 0, v[130:131]
	s_mov_b32 m0, s23
	s_nop 0
	global_load_lds_dwordx4 v[224:225], off
	s_mov_b32 m0, s42
	s_nop 0
	global_load_lds_dwordx4 v[226:227], off
	s_cmp_eq_u32 s59, 0
	s_cbranch_scc1 .Lw8_3
	s_waitcnt vmcnt(24)
	s_branch .Lwe_3

.Lwe_3:
	s_waitcnt lgkmcnt(0)
	s_barrier
	s_nop 0
	s_waitcnt lgkmcnt(0)
	v_mfma_f32_16x16x32_bf16 v[62:65], v[158:161], v[190:193], v[62:65]
	v_mfma_f32_16x16x32_bf16 v[58:61], v[166:169], v[190:193], v[58:61]
	v_mfma_f32_16x16x32_bf16 v[46:49], v[158:161], v[198:201], v[46:49]
	v_mfma_f32_16x16x32_bf16 v[42:45], v[166:169], v[198:201], v[42:45]
	v_mfma_f32_16x16x32_bf16 v[30:33], v[158:161], v[206:209], v[30:33]
	v_mfma_f32_16x16x32_bf16 v[26:29], v[166:169], v[206:209], v[26:29]
	v_mfma_f32_16x16x32_bf16 v[14:17], v[158:161], v[214:217], v[14:17]
	v_mfma_f32_16x16x32_bf16 v[10:13], v[166:169], v[214:217], v[10:13]
	v_mfma_f32_16x16x32_bf16 v[62:65], v[162:165], v[194:197], v[62:65]
	v_mfma_f32_16x16x32_bf16 v[58:61], v[170:173], v[194:197], v[58:61]
	v_mfma_f32_16x16x32_bf16 v[46:49], v[162:165], v[202:205], v[46:49]
	v_mfma_f32_16x16x32_bf16 v[42:45], v[170:173], v[202:205], v[42:45]
	v_mfma_f32_16x16x32_bf16 v[30:33], v[162:165], v[210:213], v[30:33]
	v_mfma_f32_16x16x32_bf16 v[26:29], v[170:173], v[210:213], v[26:29]
	v_mfma_f32_16x16x32_bf16 v[14:17], v[162:165], v[218:221], v[14:17]
	v_mfma_f32_16x16x32_bf16 v[10:13], v[170:173], v[218:221], v[10:13]
	s_nop 0
	s_nop 0
	v_mfma_f32_16x16x32_bf16 v[54:57], v[174:177], v[190:193], v[54:57]
	v_mfma_f32_16x16x32_bf16 v[50:53], v[182:185], v[190:193], v[50:53]
	v_mfma_f32_16x16x32_bf16 v[38:41], v[174:177], v[198:201], v[38:41]
	v_mfma_f32_16x16x32_bf16 v[34:37], v[182:185], v[198:201], v[34:37]
	v_mfma_f32_16x16x32_bf16 v[22:25], v[174:177], v[206:209], v[22:25]
	v_mfma_f32_16x16x32_bf16 v[18:21], v[182:185], v[206:209], v[18:21]
	v_mfma_f32_16x16x32_bf16 v[6:9], v[174:177], v[214:217], v[6:9]
	v_mfma_f32_16x16x32_bf16 v[2:5], v[182:185], v[214:217], v[2:5]
	v_mfma_f32_16x16x32_bf16 v[54:57], v[178:181], v[194:197], v[54:57]
	v_mfma_f32_16x16x32_bf16 v[50:53], v[186:189], v[194:197], v[50:53]
	v_mfma_f32_16x16x32_bf16 v[38:41], v[178:181], v[202:205], v[38:41]
	v_mfma_f32_16x16x32_bf16 v[34:37], v[186:189], v[202:205], v[34:37]
	v_mfma_f32_16x16x32_bf16 v[22:25], v[178:181], v[210:213], v[22:25]
	v_mfma_f32_16x16x32_bf16 v[18:21], v[186:189], v[210:213], v[18:21]
	v_mfma_f32_16x16x32_bf16 v[6:9], v[178:181], v[218:221], v[6:9]
	v_mfma_f32_16x16x32_bf16 v[2:5], v[186:189], v[218:221], v[2:5]
	s_nop 0
	s_barrier
	s_add_i32 s59, 0, 0x18000
	s_add_i32 s60, 0, 0x1c000
	v_add_u32_e32 v170, s59, v152
	v_add_u32_e32 v186, s60, v152
	ds_read_b128 v[158:161], v170
	ds_read_b128 v[162:165], v170 offset:1024
	ds_read_b128 v[166:169], v170 offset:2048
	ds_read_b128 v[170:173], v170 offset:3072
	ds_read_b128 v[174:177], v186
	ds_read_b128 v[178:181], v186 offset:1024
	ds_read_b128 v[182:185], v186 offset:2048
	ds_read_b128 v[186:189], v186 offset:3072
	s_add_u32 s34, s34, 0x40000
	s_addc_u32 s35, s35, 0
	s_mov_b32 m0, s43
	v_lshl_add_u64 v[228:229], s[34:35], 0, v[130:131]
	ds_read_b128 v[190:193], v157 offset:32768
	ds_read_b128 v[194:197], v157 offset:33792
	ds_read_b128 v[198:201], v157 offset:34816
	ds_read_b128 v[202:205], v157 offset:35840
	ds_read_b128 v[206:209], v157 offset:36864
	ds_read_b128 v[210:213], v157 offset:37888
	ds_read_b128 v[214:217], v157 offset:38912
	ds_read_b128 v[218:221], v157 offset:39936
	global_load_lds_dwordx4 v[228:229], off
	v_lshl_add_u64 v[228:229], s[34:35], 0, v[134:135]
	s_mov_b32 m0, s44
	s_nop 0
	global_load_lds_dwordx4 v[228:229], off
	s_waitcnt vmcnt(8)
	s_waitcnt lgkmcnt(0)
	s_barrier
	s_nop 0
	s_waitcnt lgkmcnt(0)
	v_mfma_f32_16x16x32_bf16 v[126:129], v[158:161], v[190:193], v[126:129]
	v_mfma_f32_16x16x32_bf16 v[122:125], v[166:169], v[190:193], v[122:125]
	v_mfma_f32_16x16x32_bf16 v[110:113], v[158:161], v[198:201], v[110:113]
	v_mfma_f32_16x16x32_bf16 v[106:109], v[166:169], v[198:201], v[106:109]
	v_mfma_f32_16x16x32_bf16 v[94:97], v[158:161], v[206:209], v[94:97]
	v_mfma_f32_16x16x32_bf16 v[90:93], v[166:169], v[206:209], v[90:93]
	v_mfma_f32_16x16x32_bf16 v[78:81], v[158:161], v[214:217], v[78:81]
	v_mfma_f32_16x16x32_bf16 v[74:77], v[166:169], v[214:217], v[74:77]
	v_mfma_f32_16x16x32_bf16 v[126:129], v[162:165], v[194:197], v[126:129]
	v_mfma_f32_16x16x32_bf16 v[122:125], v[170:173], v[194:197], v[122:125]
	v_mfma_f32_16x16x32_bf16 v[110:113], v[162:165], v[202:205], v[110:113]
	v_mfma_f32_16x16x32_bf16 v[106:109], v[170:173], v[202:205], v[106:109]
	v_mfma_f32_16x16x32_bf16 v[94:97], v[162:165], v[210:213], v[94:97]
	v_mfma_f32_16x16x32_bf16 v[90:93], v[170:173], v[210:213], v[90:93]
	v_mfma_f32_16x16x32_bf16 v[78:81], v[162:165], v[218:221], v[78:81]
	v_mfma_f32_16x16x32_bf16 v[74:77], v[170:173], v[218:221], v[74:77]
	s_nop 0
	s_nop 0
	v_mfma_f32_16x16x32_bf16 v[118:121], v[174:177], v[190:193], v[118:121]
	v_mfma_f32_16x16x32_bf16 v[114:117], v[182:185], v[190:193], v[114:117]
	v_mfma_f32_16x16x32_bf16 v[102:105], v[174:177], v[198:201], v[102:105]
	v_mfma_f32_16x16x32_bf16 v[98:101], v[182:185], v[198:201], v[98:101]
	v_mfma_f32_16x16x32_bf16 v[86:89], v[174:177], v[206:209], v[86:89]
	v_mfma_f32_16x16x32_bf16 v[82:85], v[182:185], v[206:209], v[82:85]
	v_mfma_f32_16x16x32_bf16 v[70:73], v[174:177], v[214:217], v[70:73]
	v_mfma_f32_16x16x32_bf16 v[66:69], v[182:185], v[214:217], v[66:69]
	v_mfma_f32_16x16x32_bf16 v[118:121], v[178:181], v[194:197], v[118:121]
	v_mfma_f32_16x16x32_bf16 v[114:117], v[186:189], v[194:197], v[114:117]
	v_mfma_f32_16x16x32_bf16 v[102:105], v[178:181], v[202:205], v[102:105]
	v_mfma_f32_16x16x32_bf16 v[98:101], v[186:189], v[202:205], v[98:101]
	v_mfma_f32_16x16x32_bf16 v[86:89], v[178:181], v[210:213], v[86:89]
	v_mfma_f32_16x16x32_bf16 v[82:85], v[186:189], v[210:213], v[82:85]
	v_mfma_f32_16x16x32_bf16 v[70:73], v[178:181], v[218:221], v[70:73]
	v_mfma_f32_16x16x32_bf16 v[66:69], v[186:189], v[218:221], v[66:69]
	s_nop 0
	s_barrier
	s_add_i32 s34, s59, s41
	v_lshl_add_u64 v[150:151], v[150:151], 0, s[10:11]
	s_mov_b32 m0, s34
	ds_read_b128 v[190:193], v157 offset:49152
	ds_read_b128 v[194:197], v157 offset:50176
	ds_read_b128 v[198:201], v157 offset:51200
	ds_read_b128 v[202:205], v157 offset:52224
	ds_read_b128 v[206:209], v157 offset:53248
	ds_read_b128 v[210:213], v157 offset:54272
	ds_read_b128 v[214:217], v157 offset:55296
	ds_read_b128 v[218:221], v157 offset:56320
	global_load_lds_dwordx4 v[150:151], off
	s_add_i32 m0, s34, 0x2000
	s_add_u32 s30, s30, 0x40080
	v_lshl_add_u64 v[150:151], v[222:223], 0, s[10:11]
	s_addc_u32 s31, s31, 0
	s_add_i32 s34, s60, s41
	global_load_lds_dwordx4 v[150:151], off
	v_lshl_add_u64 v[150:151], s[30:31], 0, v[132:133]
	s_mov_b32 m0, s34
	s_nop 0
	global_load_lds_dwordx4 v[150:151], off
	v_lshl_add_u64 v[150:151], s[30:31], 0, v[136:137]
	s_add_i32 m0, s34, 0x2000
	s_nop 0
	global_load_lds_dwordx4 v[150:151], off
	v_lshl_add_u64 v[150:151], v[224:225], 0, s[10:11]
	s_mov_b32 m0, s46
	s_nop 0
	global_load_lds_dwordx4 v[150:151], off
	v_lshl_add_u64 v[150:151], v[226:227], 0, s[10:11]
	s_mov_b32 m0, s47
	s_nop 0
	global_load_lds_dwordx4 v[150:151], off
	s_waitcnt vmcnt(8)
	s_waitcnt lgkmcnt(0)
	s_barrier
	s_nop 0
	s_waitcnt lgkmcnt(0)
	v_mfma_f32_16x16x32_bf16 v[62:65], v[158:161], v[190:193], v[62:65]
	v_mfma_f32_16x16x32_bf16 v[58:61], v[166:169], v[190:193], v[58:61]
	v_mfma_f32_16x16x32_bf16 v[46:49], v[158:161], v[198:201], v[46:49]
	v_mfma_f32_16x16x32_bf16 v[42:45], v[166:169], v[198:201], v[42:45]
	v_mfma_f32_16x16x32_bf16 v[30:33], v[158:161], v[206:209], v[30:33]
	v_mfma_f32_16x16x32_bf16 v[26:29], v[166:169], v[206:209], v[26:29]
	v_mfma_f32_16x16x32_bf16 v[14:17], v[158:161], v[214:217], v[14:17]
	v_mfma_f32_16x16x32_bf16 v[10:13], v[166:169], v[214:217], v[10:13]
	v_mfma_f32_16x16x32_bf16 v[62:65], v[162:165], v[194:197], v[62:65]
	v_mfma_f32_16x16x32_bf16 v[58:61], v[170:173], v[194:197], v[58:61]
	v_mfma_f32_16x16x32_bf16 v[46:49], v[162:165], v[202:205], v[46:49]
	v_mfma_f32_16x16x32_bf16 v[42:45], v[170:173], v[202:205], v[42:45]
	v_mfma_f32_16x16x32_bf16 v[30:33], v[162:165], v[210:213], v[30:33]
	v_mfma_f32_16x16x32_bf16 v[26:29], v[170:173], v[210:213], v[26:29]
	v_mfma_f32_16x16x32_bf16 v[14:17], v[162:165], v[218:221], v[14:17]
	v_mfma_f32_16x16x32_bf16 v[10:13], v[170:173], v[218:221], v[10:13]
	s_nop 0
	s_nop 0
	v_mfma_f32_16x16x32_bf16 v[54:57], v[174:177], v[190:193], v[54:57]
	v_mfma_f32_16x16x32_bf16 v[50:53], v[182:185], v[190:193], v[50:53]
	v_mfma_f32_16x16x32_bf16 v[38:41], v[174:177], v[198:201], v[38:41]
	v_mfma_f32_16x16x32_bf16 v[34:37], v[182:185], v[198:201], v[34:37]
	v_mfma_f32_16x16x32_bf16 v[22:25], v[174:177], v[206:209], v[22:25]
	v_mfma_f32_16x16x32_bf16 v[18:21], v[182:185], v[206:209], v[18:21]
	v_mfma_f32_16x16x32_bf16 v[6:9], v[174:177], v[214:217], v[6:9]
	v_mfma_f32_16x16x32_bf16 v[2:5], v[182:185], v[214:217], v[2:5]
	v_mfma_f32_16x16x32_bf16 v[54:57], v[178:181], v[194:197], v[54:57]
	v_mfma_f32_16x16x32_bf16 v[50:53], v[186:189], v[194:197], v[50:53]
	v_mfma_f32_16x16x32_bf16 v[38:41], v[178:181], v[202:205], v[38:41]
	v_mfma_f32_16x16x32_bf16 v[34:37], v[186:189], v[202:205], v[34:37]
	v_mfma_f32_16x16x32_bf16 v[22:25], v[178:181], v[210:213], v[22:25]
	v_mfma_f32_16x16x32_bf16 v[18:21], v[186:189], v[210:213], v[18:21]
	v_mfma_f32_16x16x32_bf16 v[6:9], v[178:181], v[218:221], v[6:9]
	v_mfma_f32_16x16x32_bf16 v[2:5], v[186:189], v[218:221], v[2:5]
	s_nop 0
	s_barrier
	s_add_i32 s58, s58, 2
	s_add_u32 s28, s28, 0x100
	s_addc_u32 s29, s29, 0
	s_cmp_gt_u32 s58, 13
	s_cbranch_scc0 .LBB0_891
	s_setprio 0
	s_and_b64 vcc, exec, s[12:13]
	s_cbranch_vccz .LBB0_894
	s_barrier

.Lgprio_2:
.LBB0_915:
	ds_read_b128 v[150:153], v157
	ds_read_b128 v[160:163], v157 offset:1024
	ds_read_b128 v[164:167], v157 offset:2048
	ds_read_b128 v[168:171], v157 offset:3072
	ds_read_b128 v[172:175], v158
	ds_read_b128 v[176:179], v158 offset:1024
	ds_read_b128 v[180:183], v158 offset:2048
	ds_read_b128 v[184:187], v158 offset:3072
	s_add_u32 s30, s24, s28
	s_addc_u32 s31, s25, s29
	s_add_u32 s34, s30, 0x100
	s_addc_u32 s35, s31, 0
	s_add_u32 s59, s56, s28
	s_addc_u32 s60, s57, s29
	s_cmp_eq_u32 s28, 0
	s_cselect_b64 s[30:31], -1, 0
	s_and_b64 s[30:31], s[26:27], s[30:31]
	s_cmpk_eq_i32 s28, 0x700
	v_cndmask_b32_e64 v188, 0, 1, s[30:31]
	s_cselect_b32 s35, s17, s35
	s_cselect_b32 s34, s54, s34
	v_readfirstlane_b32 s61, v188
	s_cselect_b32 s31, s15, s60
	s_cselect_b32 s30, s55, s59
	v_lshl_add_u64 v[220:221], v[148:149], 0, s[28:29]
	s_add_i32 m0, s23, 0xc000
	ds_read_b128 v[188:191], v159
	ds_read_b128 v[192:195], v159 offset:1024
	ds_read_b128 v[196:199], v159 offset:2048
	ds_read_b128 v[200:203], v159 offset:3072
	ds_read_b128 v[204:207], v159 offset:4096
	ds_read_b128 v[208:211], v159 offset:5120
	ds_read_b128 v[212:215], v159 offset:6144
	ds_read_b128 v[216:219], v159 offset:7168
	global_load_lds_dwordx4 v[220:221], off
	v_lshl_add_u64 v[220:221], v[146:147], 0, s[28:29]
	s_add_i32 m0, s23, 0xe000
	s_and_b32 s59, s61, 1
	global_load_lds_dwordx4 v[220:221], off
	s_cmp_eq_u32 s59, 0
	s_cbranch_scc1 .Lw8_4
	s_waitcnt vmcnt(24)
	s_branch .Lwe_4

.Lwe_4:
	s_waitcnt lgkmcnt(0)
	s_barrier
	s_nop 0
	s_waitcnt lgkmcnt(0)
	v_mfma_f32_16x16x32_bf16 v[126:129], v[150:153], v[188:191], v[126:129]
	v_mfma_f32_16x16x32_bf16 v[122:125], v[164:167], v[188:191], v[122:125]
	v_mfma_f32_16x16x32_bf16 v[110:113], v[150:153], v[196:199], v[110:113]
	v_mfma_f32_16x16x32_bf16 v[106:109], v[164:167], v[196:199], v[106:109]
	v_mfma_f32_16x16x32_bf16 v[94:97], v[150:153], v[204:207], v[94:97]
	v_mfma_f32_16x16x32_bf16 v[90:93], v[164:167], v[204:207], v[90:93]
	v_mfma_f32_16x16x32_bf16 v[78:81], v[150:153], v[212:215], v[78:81]
	v_mfma_f32_16x16x32_bf16 v[74:77], v[164:167], v[212:215], v[74:77]
	v_mfma_f32_16x16x32_bf16 v[126:129], v[160:163], v[192:195], v[126:129]
	v_mfma_f32_16x16x32_bf16 v[122:125], v[168:171], v[192:195], v[122:125]
	v_mfma_f32_16x16x32_bf16 v[110:113], v[160:163], v[200:203], v[110:113]
	v_mfma_f32_16x16x32_bf16 v[106:109], v[168:171], v[200:203], v[106:109]
	v_mfma_f32_16x16x32_bf16 v[94:97], v[160:163], v[208:211], v[94:97]
	v_mfma_f32_16x16x32_bf16 v[90:93], v[168:171], v[208:211], v[90:93]
	v_mfma_f32_16x16x32_bf16 v[78:81], v[160:163], v[216:219], v[78:81]
	v_mfma_f32_16x16x32_bf16 v[74:77], v[168:171], v[216:219], v[74:77]
	s_nop 0
	s_nop 0
	v_mfma_f32_16x16x32_bf16 v[118:121], v[172:175], v[188:191], v[118:121]
	v_mfma_f32_16x16x32_bf16 v[114:117], v[180:183], v[188:191], v[114:117]
	v_mfma_f32_16x16x32_bf16 v[102:105], v[172:175], v[196:199], v[102:105]
	v_mfma_f32_16x16x32_bf16 v[98:101], v[180:183], v[196:199], v[98:101]
	v_mfma_f32_16x16x32_bf16 v[86:89], v[172:175], v[204:207], v[86:89]
	v_mfma_f32_16x16x32_bf16 v[82:85], v[180:183], v[204:207], v[82:85]
	v_mfma_f32_16x16x32_bf16 v[70:73], v[172:175], v[212:215], v[70:73]
	v_mfma_f32_16x16x32_bf16 v[66:69], v[180:183], v[212:215], v[66:69]
	v_mfma_f32_16x16x32_bf16 v[118:121], v[176:179], v[192:195], v[118:121]
	v_mfma_f32_16x16x32_bf16 v[114:117], v[184:187], v[192:195], v[114:117]
	v_mfma_f32_16x16x32_bf16 v[102:105], v[176:179], v[200:203], v[102:105]
	v_mfma_f32_16x16x32_bf16 v[98:101], v[184:187], v[200:203], v[98:101]
	v_mfma_f32_16x16x32_bf16 v[86:89], v[176:179], v[208:211], v[86:89]
	v_mfma_f32_16x16x32_bf16 v[82:85], v[184:187], v[208:211], v[82:85]
	v_mfma_f32_16x16x32_bf16 v[70:73], v[176:179], v[216:219], v[70:73]
	v_mfma_f32_16x16x32_bf16 v[66:69], v[184:187], v[216:219], v[66:69]
	s_nop 0
	s_barrier
	s_add_i32 s60, s50, s41
	v_lshl_add_u64 v[220:221], s[30:31], 0, v[132:133]
	s_mov_b32 m0, s60
	ds_read_b128 v[188:191], v159 offset:16384
	ds_read_b128 v[192:195], v159 offset:17408
	ds_read_b128 v[196:199], v159 offset:18432
	ds_read_b128 v[200:203], v159 offset:19456
	ds_read_b128 v[204:207], v159 offset:20480
	ds_read_b128 v[208:211], v159 offset:21504
	ds_read_b128 v[212:215], v159 offset:22528
	ds_read_b128 v[216:219], v159 offset:23552
	global_load_lds_dwordx4 v[220:221], off
	s_add_i32 m0, s60, 0x2000
	s_add_u32 s60, s30, 0x40000
	v_lshl_add_u64 v[222:223], s[30:31], 0, v[136:137]
	s_addc_u32 s61, s31, 0
	s_add_i32 s62, s51, s41
	global_load_lds_dwordx4 v[222:223], off
	v_lshl_add_u64 v[224:225], s[60:61], 0, v[132:133]
	s_mov_b32 m0, s62
	v_lshl_add_u64 v[226:227], s[34:35], 0, v[134:135]
	global_load_lds_dwordx4 v[224:225], off
	v_lshl_add_u64 v[224:225], s[60:61], 0, v[136:137]
	s_add_i32 m0, s62, 0x2000
	s_nop 0
	global_load_lds_dwordx4 v[224:225], off
	v_lshl_add_u64 v[224:225], s[34:35], 0, v[130:131]
	s_mov_b32 m0, s23
	s_nop 0
	global_load_lds_dwordx4 v[224:225], off
	s_mov_b32 m0, s42
	s_nop 0
	global_load_lds_dwordx4 v[226:227], off
	s_cmp_eq_u32 s59, 0
	s_cbranch_scc1 .Lw8_5
	s_waitcnt vmcnt(24)
	s_branch .Lwe_5

.Lwe_5:
	s_waitcnt lgkmcnt(0)
	s_barrier
	s_nop 0
	s_waitcnt lgkmcnt(0)
	v_mfma_f32_16x16x32_bf16 v[62:65], v[150:153], v[188:191], v[62:65]
	v_mfma_f32_16x16x32_bf16 v[58:61], v[164:167], v[188:191], v[58:61]
	v_mfma_f32_16x16x32_bf16 v[46:49], v[150:153], v[196:199], v[46:49]
	v_mfma_f32_16x16x32_bf16 v[42:45], v[164:167], v[196:199], v[42:45]
	v_mfma_f32_16x16x32_bf16 v[30:33], v[150:153], v[204:207], v[30:33]
	v_mfma_f32_16x16x32_bf16 v[26:29], v[164:167], v[204:207], v[26:29]
	v_mfma_f32_16x16x32_bf16 v[14:17], v[150:153], v[212:215], v[14:17]
	v_mfma_f32_16x16x32_bf16 v[10:13], v[164:167], v[212:215], v[10:13]
	v_mfma_f32_16x16x32_bf16 v[62:65], v[160:163], v[192:195], v[62:65]
	v_mfma_f32_16x16x32_bf16 v[58:61], v[168:171], v[192:195], v[58:61]
	v_mfma_f32_16x16x32_bf16 v[46:49], v[160:163], v[200:203], v[46:49]
	v_mfma_f32_16x16x32_bf16 v[42:45], v[168:171], v[200:203], v[42:45]
	v_mfma_f32_16x16x32_bf16 v[30:33], v[160:163], v[208:211], v[30:33]
	v_mfma_f32_16x16x32_bf16 v[26:29], v[168:171], v[208:211], v[26:29]
	v_mfma_f32_16x16x32_bf16 v[14:17], v[160:163], v[216:219], v[14:17]
	v_mfma_f32_16x16x32_bf16 v[10:13], v[168:171], v[216:219], v[10:13]
	s_nop 0
	s_nop 0
	v_mfma_f32_16x16x32_bf16 v[54:57], v[172:175], v[188:191], v[54:57]
	v_mfma_f32_16x16x32_bf16 v[50:53], v[180:183], v[188:191], v[50:53]
	v_mfma_f32_16x16x32_bf16 v[38:41], v[172:175], v[196:199], v[38:41]
	v_mfma_f32_16x16x32_bf16 v[34:37], v[180:183], v[196:199], v[34:37]
	v_mfma_f32_16x16x32_bf16 v[22:25], v[172:175], v[204:207], v[22:25]
	v_mfma_f32_16x16x32_bf16 v[18:21], v[180:183], v[204:207], v[18:21]
	v_mfma_f32_16x16x32_bf16 v[6:9], v[172:175], v[212:215], v[6:9]
	v_mfma_f32_16x16x32_bf16 v[2:5], v[180:183], v[212:215], v[2:5]
	v_mfma_f32_16x16x32_bf16 v[54:57], v[176:179], v[192:195], v[54:57]
	v_mfma_f32_16x16x32_bf16 v[50:53], v[184:187], v[192:195], v[50:53]
	v_mfma_f32_16x16x32_bf16 v[38:41], v[176:179], v[200:203], v[38:41]
	v_mfma_f32_16x16x32_bf16 v[34:37], v[184:187], v[200:203], v[34:37]
	v_mfma_f32_16x16x32_bf16 v[22:25], v[176:179], v[208:211], v[22:25]
	v_mfma_f32_16x16x32_bf16 v[18:21], v[184:187], v[208:211], v[18:21]
	v_mfma_f32_16x16x32_bf16 v[6:9], v[176:179], v[216:219], v[6:9]
	v_mfma_f32_16x16x32_bf16 v[2:5], v[184:187], v[216:219], v[2:5]
	s_nop 0
	s_barrier
	s_add_i32 s59, 0, 0x18000
	s_add_i32 s60, 0, 0x1c000
	v_add_u32_e32 v168, s59, v155
	v_add_u32_e32 v184, s60, v155
	ds_read_b128 v[150:153], v168
	ds_read_b128 v[160:163], v168 offset:1024
	ds_read_b128 v[164:167], v168 offset:2048
	ds_read_b128 v[168:171], v168 offset:3072
	ds_read_b128 v[172:175], v184
	ds_read_b128 v[176:179], v184 offset:1024
	ds_read_b128 v[180:183], v184 offset:2048
	ds_read_b128 v[184:187], v184 offset:3072
	s_add_u32 s34, s34, 0x40000
	s_addc_u32 s35, s35, 0
	s_mov_b32 m0, s43
	v_lshl_add_u64 v[228:229], s[34:35], 0, v[130:131]
	ds_read_b128 v[188:191], v159 offset:32768
	ds_read_b128 v[192:195], v159 offset:33792
	ds_read_b128 v[196:199], v159 offset:34816
	ds_read_b128 v[200:203], v159 offset:35840
	ds_read_b128 v[204:207], v159 offset:36864
	ds_read_b128 v[208:211], v159 offset:37888
	ds_read_b128 v[212:215], v159 offset:38912
	ds_read_b128 v[216:219], v159 offset:39936
	global_load_lds_dwordx4 v[228:229], off
	v_lshl_add_u64 v[228:229], s[34:35], 0, v[134:135]
	s_mov_b32 m0, s44
	s_nop 0
	global_load_lds_dwordx4 v[228:229], off
	s_waitcnt vmcnt(8)
	s_waitcnt lgkmcnt(0)
	s_barrier
	s_nop 0
	s_waitcnt lgkmcnt(0)
	v_mfma_f32_16x16x32_bf16 v[126:129], v[150:153], v[188:191], v[126:129]
	v_mfma_f32_16x16x32_bf16 v[122:125], v[164:167], v[188:191], v[122:125]
	v_mfma_f32_16x16x32_bf16 v[110:113], v[150:153], v[196:199], v[110:113]
	v_mfma_f32_16x16x32_bf16 v[106:109], v[164:167], v[196:199], v[106:109]
	v_mfma_f32_16x16x32_bf16 v[94:97], v[150:153], v[204:207], v[94:97]
	v_mfma_f32_16x16x32_bf16 v[90:93], v[164:167], v[204:207], v[90:93]
	v_mfma_f32_16x16x32_bf16 v[78:81], v[150:153], v[212:215], v[78:81]
	v_mfma_f32_16x16x32_bf16 v[74:77], v[164:167], v[212:215], v[74:77]
	v_mfma_f32_16x16x32_bf16 v[126:129], v[160:163], v[192:195], v[126:129]
	v_mfma_f32_16x16x32_bf16 v[122:125], v[168:171], v[192:195], v[122:125]
	v_mfma_f32_16x16x32_bf16 v[110:113], v[160:163], v[200:203], v[110:113]
	v_mfma_f32_16x16x32_bf16 v[106:109], v[168:171], v[200:203], v[106:109]
	v_mfma_f32_16x16x32_bf16 v[94:97], v[160:163], v[208:211], v[94:97]
	v_mfma_f32_16x16x32_bf16 v[90:93], v[168:171], v[208:211], v[90:93]
	v_mfma_f32_16x16x32_bf16 v[78:81], v[160:163], v[216:219], v[78:81]
	v_mfma_f32_16x16x32_bf16 v[74:77], v[168:171], v[216:219], v[74:77]
	s_nop 0
	s_nop 0
	v_mfma_f32_16x16x32_bf16 v[118:121], v[172:175], v[188:191], v[118:121]
	v_mfma_f32_16x16x32_bf16 v[114:117], v[180:183], v[188:191], v[114:117]
	v_mfma_f32_16x16x32_bf16 v[102:105], v[172:175], v[196:199], v[102:105]
	v_mfma_f32_16x16x32_bf16 v[98:101], v[180:183], v[196:199], v[98:101]
	v_mfma_f32_16x16x32_bf16 v[86:89], v[172:175], v[204:207], v[86:89]
	v_mfma_f32_16x16x32_bf16 v[82:85], v[180:183], v[204:207], v[82:85]
	v_mfma_f32_16x16x32_bf16 v[70:73], v[172:175], v[212:215], v[70:73]
	v_mfma_f32_16x16x32_bf16 v[66:69], v[180:183], v[212:215], v[66:69]
	v_mfma_f32_16x16x32_bf16 v[118:121], v[176:179], v[192:195], v[118:121]
	v_mfma_f32_16x16x32_bf16 v[114:117], v[184:187], v[192:195], v[114:117]
	v_mfma_f32_16x16x32_bf16 v[102:105], v[176:179], v[200:203], v[102:105]
	v_mfma_f32_16x16x32_bf16 v[98:101], v[184:187], v[200:203], v[98:101]
	v_mfma_f32_16x16x32_bf16 v[86:89], v[176:179], v[208:211], v[86:89]
	v_mfma_f32_16x16x32_bf16 v[82:85], v[184:187], v[208:211], v[82:85]
	v_mfma_f32_16x16x32_bf16 v[70:73], v[176:179], v[216:219], v[70:73]
	v_mfma_f32_16x16x32_bf16 v[66:69], v[184:187], v[216:219], v[66:69]
	s_nop 0
	s_barrier
	s_add_i32 s34, s59, s41
	v_lshl_add_u64 v[220:221], v[220:221], 0, s[10:11]
	s_mov_b32 m0, s34
	ds_read_b128 v[188:191], v159 offset:49152
	ds_read_b128 v[192:195], v159 offset:50176
	ds_read_b128 v[196:199], v159 offset:51200
	ds_read_b128 v[200:203], v159 offset:52224
	ds_read_b128 v[204:207], v159 offset:53248
	ds_read_b128 v[208:211], v159 offset:54272
	ds_read_b128 v[212:215], v159 offset:55296
	ds_read_b128 v[216:219], v159 offset:56320
	global_load_lds_dwordx4 v[220:221], off
	s_add_i32 m0, s34, 0x2000
	s_add_u32 s30, s30, 0x40080
	v_lshl_add_u64 v[220:221], v[222:223], 0, s[10:11]
	s_addc_u32 s31, s31, 0
	s_add_i32 s34, s60, s41
	global_load_lds_dwordx4 v[220:221], off
	v_lshl_add_u64 v[220:221], s[30:31], 0, v[132:133]
	s_mov_b32 m0, s34
	s_nop 0
	global_load_lds_dwordx4 v[220:221], off
	v_lshl_add_u64 v[220:221], s[30:31], 0, v[136:137]
	s_add_i32 m0, s34, 0x2000
	s_nop 0
	global_load_lds_dwordx4 v[220:221], off
	v_lshl_add_u64 v[220:221], v[224:225], 0, s[10:11]
	s_mov_b32 m0, s46
	s_nop 0
	global_load_lds_dwordx4 v[220:221], off
	v_lshl_add_u64 v[220:221], v[226:227], 0, s[10:11]
	s_mov_b32 m0, s47
	s_nop 0
	global_load_lds_dwordx4 v[220:221], off
	s_waitcnt vmcnt(8)
	s_waitcnt lgkmcnt(0)
	s_barrier
	s_nop 0
	s_waitcnt lgkmcnt(0)
	v_mfma_f32_16x16x32_bf16 v[62:65], v[150:153], v[188:191], v[62:65]
	v_mfma_f32_16x16x32_bf16 v[58:61], v[164:167], v[188:191], v[58:61]
	v_mfma_f32_16x16x32_bf16 v[46:49], v[150:153], v[196:199], v[46:49]
	v_mfma_f32_16x16x32_bf16 v[42:45], v[164:167], v[196:199], v[42:45]
	v_mfma_f32_16x16x32_bf16 v[30:33], v[150:153], v[204:207], v[30:33]
	v_mfma_f32_16x16x32_bf16 v[26:29], v[164:167], v[204:207], v[26:29]
	v_mfma_f32_16x16x32_bf16 v[14:17], v[150:153], v[212:215], v[14:17]
	v_mfma_f32_16x16x32_bf16 v[10:13], v[164:167], v[212:215], v[10:13]
	v_mfma_f32_16x16x32_bf16 v[62:65], v[160:163], v[192:195], v[62:65]
	v_mfma_f32_16x16x32_bf16 v[58:61], v[168:171], v[192:195], v[58:61]
	v_mfma_f32_16x16x32_bf16 v[46:49], v[160:163], v[200:203], v[46:49]
	v_mfma_f32_16x16x32_bf16 v[42:45], v[168:171], v[200:203], v[42:45]
	v_mfma_f32_16x16x32_bf16 v[30:33], v[160:163], v[208:211], v[30:33]
	v_mfma_f32_16x16x32_bf16 v[26:29], v[168:171], v[208:211], v[26:29]
	v_mfma_f32_16x16x32_bf16 v[14:17], v[160:163], v[216:219], v[14:17]
	v_mfma_f32_16x16x32_bf16 v[10:13], v[168:171], v[216:219], v[10:13]
	s_nop 0
	s_nop 0
	v_mfma_f32_16x16x32_bf16 v[54:57], v[172:175], v[188:191], v[54:57]
	v_mfma_f32_16x16x32_bf16 v[50:53], v[180:183], v[188:191], v[50:53]
	v_mfma_f32_16x16x32_bf16 v[38:41], v[172:175], v[196:199], v[38:41]
	v_mfma_f32_16x16x32_bf16 v[34:37], v[180:183], v[196:199], v[34:37]
	v_mfma_f32_16x16x32_bf16 v[22:25], v[172:175], v[204:207], v[22:25]
	v_mfma_f32_16x16x32_bf16 v[18:21], v[180:183], v[204:207], v[18:21]
	v_mfma_f32_16x16x32_bf16 v[6:9], v[172:175], v[212:215], v[6:9]
	v_mfma_f32_16x16x32_bf16 v[2:5], v[180:183], v[212:215], v[2:5]
	v_mfma_f32_16x16x32_bf16 v[54:57], v[176:179], v[192:195], v[54:57]
	v_mfma_f32_16x16x32_bf16 v[50:53], v[184:187], v[192:195], v[50:53]
	v_mfma_f32_16x16x32_bf16 v[38:41], v[176:179], v[200:203], v[38:41]
	v_mfma_f32_16x16x32_bf16 v[34:37], v[184:187], v[200:203], v[34:37]
	v_mfma_f32_16x16x32_bf16 v[22:25], v[176:179], v[208:211], v[22:25]
	v_mfma_f32_16x16x32_bf16 v[18:21], v[184:187], v[208:211], v[18:21]
	v_mfma_f32_16x16x32_bf16 v[6:9], v[176:179], v[216:219], v[6:9]
	v_mfma_f32_16x16x32_bf16 v[2:5], v[184:187], v[216:219], v[2:5]
	s_nop 0
	s_barrier
	s_add_i32 s58, s58, 2
	s_add_u32 s28, s28, 0x100
	s_addc_u32 s29, s29, 0
	s_cmp_gt_u32 s58, 13
	s_cbranch_scc0 .LBB0_915
	s_setprio 0
	s_and_b64 vcc, exec, s[12:13]
	s_cbranch_vccz .LBB0_918
	s_barrier

.LBB0_1008:
	s_ashr_i32 s21, s20, 31
	s_lshl_b64 s[22:23], s[20:21], 20
	s_add_u32 s22, s41, s22
	s_addc_u32 s23, s42, s23
	s_and_b64 s[24:25], s[4:5], exec
	s_cselect_b32 s21, s23, s29
	s_cselect_b32 s61, s22, s28
	s_ashr_i32 s19, s18, 31
	s_lshl_b64 s[24:25], s[18:19], 20
	s_add_u32 s24, s43, s24
	s_addc_u32 s25, s44, s25
	s_and_b64 s[36:37], s[4:5], exec
	s_cselect_b32 s19, s25, s35
	s_cselect_b32 s62, s24, s34
	s_cmp_lg_u32 s30, 0
	s_cselect_b64 s[30:31], -1, 0
	s_add_u32 s63, s34, 0x100
	v_mov_b32_e32 v2, 0
	s_addc_u32 s64, s35, 0
	v_lshl_add_u64 v[146:147], s[28:29], 0, v[138:139]
	v_lshl_add_u64 v[148:149], s[28:29], 0, v[140:141]
	s_mov_b32 s65, -2
	s_mov_b64 s[34:35], 0
	v_mov_b32_e32 v3, v2
	v_mov_b32_e32 v4, v2
	v_mov_b32_e32 v5, v2
	v_mov_b32_e32 v6, v2
	v_mov_b32_e32 v7, v2
	v_mov_b32_e32 v8, v2
	v_mov_b32_e32 v9, v2
	v_mov_b32_e32 v10, v2
	v_mov_b32_e32 v11, v2
	v_mov_b32_e32 v12, v2
	v_mov_b32_e32 v13, v2
	v_mov_b32_e32 v18, v2
	v_mov_b32_e32 v19, v2
	v_mov_b32_e32 v20, v2
	v_mov_b32_e32 v21, v2
	v_mov_b32_e32 v26, v2
	v_mov_b32_e32 v27, v2
	v_mov_b32_e32 v28, v2
	v_mov_b32_e32 v29, v2
	v_mov_b32_e32 v34, v2
	v_mov_b32_e32 v35, v2
	v_mov_b32_e32 v36, v2
	v_mov_b32_e32 v37, v2
	v_mov_b32_e32 v42, v2
	v_mov_b32_e32 v43, v2
	v_mov_b32_e32 v44, v2
	v_mov_b32_e32 v45, v2
	v_mov_b32_e32 v50, v2
	v_mov_b32_e32 v51, v2
	v_mov_b32_e32 v52, v2
	v_mov_b32_e32 v53, v2
	v_mov_b32_e32 v14, v2
	v_mov_b32_e32 v15, v2
	v_mov_b32_e32 v16, v2
	v_mov_b32_e32 v17, v2
	v_mov_b32_e32 v22, v2
	v_mov_b32_e32 v23, v2
	v_mov_b32_e32 v24, v2
	v_mov_b32_e32 v25, v2
	v_mov_b32_e32 v30, v2
	v_mov_b32_e32 v31, v2
	v_mov_b32_e32 v32, v2
	v_mov_b32_e32 v33, v2
	v_mov_b32_e32 v38, v2
	v_mov_b32_e32 v39, v2
	v_mov_b32_e32 v40, v2
	v_mov_b32_e32 v41, v2
	v_mov_b32_e32 v46, v2
	v_mov_b32_e32 v47, v2
	v_mov_b32_e32 v48, v2
	v_mov_b32_e32 v49, v2
	v_mov_b32_e32 v54, v2
	v_mov_b32_e32 v55, v2
	v_mov_b32_e32 v56, v2
	v_mov_b32_e32 v57, v2
	v_mov_b32_e32 v58, v2
	v_mov_b32_e32 v59, v2
	v_mov_b32_e32 v60, v2
	v_mov_b32_e32 v61, v2
	v_mov_b32_e32 v62, v2
	v_mov_b32_e32 v63, v2
	v_mov_b32_e32 v64, v2
	v_mov_b32_e32 v65, v2
	v_mov_b32_e32 v66, v2
	v_mov_b32_e32 v67, v2
	v_mov_b32_e32 v68, v2
	v_mov_b32_e32 v69, v2
	v_mov_b32_e32 v70, v2
	v_mov_b32_e32 v71, v2
	v_mov_b32_e32 v72, v2
	v_mov_b32_e32 v73, v2
	v_mov_b32_e32 v74, v2
	v_mov_b32_e32 v75, v2
	v_mov_b32_e32 v76, v2
	v_mov_b32_e32 v77, v2
	v_mov_b32_e32 v82, v2
	v_mov_b32_e32 v83, v2
	v_mov_b32_e32 v84, v2
	v_mov_b32_e32 v85, v2
	v_mov_b32_e32 v90, v2
	v_mov_b32_e32 v91, v2
	v_mov_b32_e32 v92, v2
	v_mov_b32_e32 v93, v2
	v_mov_b32_e32 v98, v2
	v_mov_b32_e32 v99, v2
	v_mov_b32_e32 v100, v2
	v_mov_b32_e32 v101, v2
	v_mov_b32_e32 v106, v2
	v_mov_b32_e32 v107, v2
	v_mov_b32_e32 v108, v2
	v_mov_b32_e32 v109, v2
	v_mov_b32_e32 v114, v2
	v_mov_b32_e32 v115, v2
	v_mov_b32_e32 v116, v2
	v_mov_b32_e32 v117, v2
	v_mov_b32_e32 v78, v2
	v_mov_b32_e32 v79, v2
	v_mov_b32_e32 v80, v2
	v_mov_b32_e32 v81, v2
	v_mov_b32_e32 v86, v2
	v_mov_b32_e32 v87, v2
	v_mov_b32_e32 v88, v2
	v_mov_b32_e32 v89, v2
	v_mov_b32_e32 v94, v2
	v_mov_b32_e32 v95, v2
	v_mov_b32_e32 v96, v2
	v_mov_b32_e32 v97, v2
	v_mov_b32_e32 v102, v2
	v_mov_b32_e32 v103, v2
	v_mov_b32_e32 v104, v2
	v_mov_b32_e32 v105, v2
	v_mov_b32_e32 v110, v2
	v_mov_b32_e32 v111, v2
	v_mov_b32_e32 v112, v2
	v_mov_b32_e32 v113, v2
	v_mov_b32_e32 v118, v2
	v_mov_b32_e32 v119, v2
	v_mov_b32_e32 v120, v2
	v_mov_b32_e32 v121, v2
	v_mov_b32_e32 v122, v2
	v_mov_b32_e32 v123, v2
	v_mov_b32_e32 v124, v2
	v_mov_b32_e32 v125, v2
	v_mov_b32_e32 v126, v2
	v_mov_b32_e32 v127, v2
	v_mov_b32_e32 v128, v2
	v_mov_b32_e32 v129, v2
	v_readfirstlane_b32 s98, v154
	s_lshr_b32 s98, s98, 8
	s_cmp_eq_u32 s98, 0
	s_cbranch_scc1 .Lgprio_3
	s_setprio 1
.Lgprio_3:
.LBB0_1009:
	ds_read_b128 v[156:159], v152
	ds_read_b128 v[160:163], v152 offset:1024
	ds_read_b128 v[164:167], v152 offset:2048
	ds_read_b128 v[168:171], v152 offset:3072
	ds_read_b128 v[172:175], v153
	ds_read_b128 v[176:179], v153 offset:1024
	ds_read_b128 v[180:183], v153 offset:2048
	ds_read_b128 v[184:187], v153 offset:3072
	s_add_u32 s36, s28, s34
	s_addc_u32 s37, s29, s35
	s_add_u32 s38, s36, 0x100
	s_addc_u32 s39, s37, 0
	s_add_u32 s66, s63, s34
	s_addc_u32 s67, s64, s35
	s_cmp_eq_u32 s34, 0
	s_cselect_b64 s[36:37], -1, 0
	s_and_b64 s[36:37], s[30:31], s[36:37]
	s_cmpk_eq_i32 s34, 0xf00
	v_cndmask_b32_e64 v188, 0, 1, s[36:37]
	s_cselect_b32 s39, s21, s39
	s_cselect_b32 s38, s61, s38
	v_readfirstlane_b32 s68, v188
	s_cselect_b32 s37, s19, s67
	s_cselect_b32 s36, s62, s66
	v_lshl_add_u64 v[220:221], v[148:149], 0, s[34:35]
	s_add_i32 m0, s27, 0xc000
	ds_read_b128 v[188:191], v155
	ds_read_b128 v[192:195], v155 offset:1024
	ds_read_b128 v[196:199], v155 offset:2048
	ds_read_b128 v[200:203], v155 offset:3072
	ds_read_b128 v[204:207], v155 offset:4096
	ds_read_b128 v[208:211], v155 offset:5120
	ds_read_b128 v[212:215], v155 offset:6144
	ds_read_b128 v[216:219], v155 offset:7168
	global_load_lds_dwordx4 v[220:221], off
	v_lshl_add_u64 v[220:221], v[146:147], 0, s[34:35]
	s_add_i32 m0, s27, 0xe000
	s_and_b32 s68, s68, 1
	global_load_lds_dwordx4 v[220:221], off
	s_cmp_eq_u32 s68, 0
	s_cbranch_scc1 .Lw8_6
	s_waitcnt vmcnt(24)
	s_branch .Lwe_6

.Lwe_6:
	s_waitcnt lgkmcnt(0)
	s_barrier
	s_nop 0
	s_waitcnt lgkmcnt(0)
	v_mfma_f32_16x16x32_bf16 v[126:129], v[156:159], v[188:191], v[126:129]
	v_mfma_f32_16x16x32_bf16 v[122:125], v[164:167], v[188:191], v[122:125]
	v_mfma_f32_16x16x32_bf16 v[118:121], v[156:159], v[196:199], v[118:121]
	v_mfma_f32_16x16x32_bf16 v[110:113], v[164:167], v[196:199], v[110:113]
	v_mfma_f32_16x16x32_bf16 v[102:105], v[156:159], v[204:207], v[102:105]
	v_mfma_f32_16x16x32_bf16 v[94:97], v[164:167], v[204:207], v[94:97]
	v_mfma_f32_16x16x32_bf16 v[86:89], v[156:159], v[212:215], v[86:89]
	v_mfma_f32_16x16x32_bf16 v[78:81], v[164:167], v[212:215], v[78:81]
	v_mfma_f32_16x16x32_bf16 v[126:129], v[160:163], v[192:195], v[126:129]
	v_mfma_f32_16x16x32_bf16 v[122:125], v[168:171], v[192:195], v[122:125]
	v_mfma_f32_16x16x32_bf16 v[118:121], v[160:163], v[200:203], v[118:121]
	v_mfma_f32_16x16x32_bf16 v[110:113], v[168:171], v[200:203], v[110:113]
	v_mfma_f32_16x16x32_bf16 v[102:105], v[160:163], v[208:211], v[102:105]
	v_mfma_f32_16x16x32_bf16 v[94:97], v[168:171], v[208:211], v[94:97]
	v_mfma_f32_16x16x32_bf16 v[86:89], v[160:163], v[216:219], v[86:89]
	v_mfma_f32_16x16x32_bf16 v[78:81], v[168:171], v[216:219], v[78:81]
	s_nop 0
	s_nop 0
	v_mfma_f32_16x16x32_bf16 v[114:117], v[172:175], v[188:191], v[114:117]
	v_mfma_f32_16x16x32_bf16 v[106:109], v[180:183], v[188:191], v[106:109]
	v_mfma_f32_16x16x32_bf16 v[98:101], v[172:175], v[196:199], v[98:101]
	v_mfma_f32_16x16x32_bf16 v[90:93], v[180:183], v[196:199], v[90:93]
	v_mfma_f32_16x16x32_bf16 v[82:85], v[172:175], v[204:207], v[82:85]
	v_mfma_f32_16x16x32_bf16 v[74:77], v[180:183], v[204:207], v[74:77]
	v_mfma_f32_16x16x32_bf16 v[70:73], v[172:175], v[212:215], v[70:73]
	v_mfma_f32_16x16x32_bf16 v[66:69], v[180:183], v[212:215], v[66:69]
	v_mfma_f32_16x16x32_bf16 v[114:117], v[176:179], v[192:195], v[114:117]
	v_mfma_f32_16x16x32_bf16 v[106:109], v[184:187], v[192:195], v[106:109]
	v_mfma_f32_16x16x32_bf16 v[98:101], v[176:179], v[200:203], v[98:101]
	v_mfma_f32_16x16x32_bf16 v[90:93], v[184:187], v[200:203], v[90:93]
	v_mfma_f32_16x16x32_bf16 v[82:85], v[176:179], v[208:211], v[82:85]
	v_mfma_f32_16x16x32_bf16 v[74:77], v[184:187], v[208:211], v[74:77]
	v_mfma_f32_16x16x32_bf16 v[70:73], v[176:179], v[216:219], v[70:73]
	v_mfma_f32_16x16x32_bf16 v[66:69], v[184:187], v[216:219], v[66:69]
	s_nop 0
	s_barrier
	s_add_i32 s66, s53, s45
	v_lshl_add_u64 v[220:221], s[36:37], 0, v[132:133]
	s_mov_b32 m0, s66
	ds_read_b128 v[188:191], v155 offset:16384
	ds_read_b128 v[192:195], v155 offset:17408
	ds_read_b128 v[196:199], v155 offset:18432
	ds_read_b128 v[200:203], v155 offset:19456
	ds_read_b128 v[204:207], v155 offset:20480
	ds_read_b128 v[208:211], v155 offset:21504
	ds_read_b128 v[212:215], v155 offset:22528
	ds_read_b128 v[216:219], v155 offset:23552
	global_load_lds_dwordx4 v[220:221], off
	s_add_i32 m0, s66, 0x2000
	s_add_u32 s66, s36, 0x80000
	v_lshl_add_u64 v[222:223], s[36:37], 0, v[136:137]
	s_addc_u32 s67, s37, 0
	s_add_i32 s69, s54, s45
	global_load_lds_dwordx4 v[222:223], off
	v_lshl_add_u64 v[224:225], s[66:67], 0, v[132:133]
	s_mov_b32 m0, s69
	v_lshl_add_u64 v[226:227], s[38:39], 0, v[134:135]
	global_load_lds_dwordx4 v[224:225], off
	v_lshl_add_u64 v[224:225], s[66:67], 0, v[136:137]
	s_add_i32 m0, s69, 0x2000
	s_nop 0
	global_load_lds_dwordx4 v[224:225], off
	v_lshl_add_u64 v[224:225], s[38:39], 0, v[130:131]
	s_mov_b32 m0, s27
	s_nop 0
	global_load_lds_dwordx4 v[224:225], off
	s_mov_b32 m0, s46
	s_nop 0
	global_load_lds_dwordx4 v[226:227], off
	s_cmp_eq_u32 s68, 0
	s_cbranch_scc1 .Lw8_7
	s_waitcnt vmcnt(24)
	s_branch .Lwe_7

.Lwe_7:
	s_waitcnt lgkmcnt(0)
	s_barrier
	s_nop 0
	s_waitcnt lgkmcnt(0)
	v_mfma_f32_16x16x32_bf16 v[62:65], v[156:159], v[188:191], v[62:65]
	v_mfma_f32_16x16x32_bf16 v[58:61], v[164:167], v[188:191], v[58:61]
	v_mfma_f32_16x16x32_bf16 v[54:57], v[156:159], v[196:199], v[54:57]
	v_mfma_f32_16x16x32_bf16 v[46:49], v[164:167], v[196:199], v[46:49]
	v_mfma_f32_16x16x32_bf16 v[38:41], v[156:159], v[204:207], v[38:41]
	v_mfma_f32_16x16x32_bf16 v[30:33], v[164:167], v[204:207], v[30:33]
	v_mfma_f32_16x16x32_bf16 v[22:25], v[156:159], v[212:215], v[22:25]
	v_mfma_f32_16x16x32_bf16 v[14:17], v[164:167], v[212:215], v[14:17]
	v_mfma_f32_16x16x32_bf16 v[62:65], v[160:163], v[192:195], v[62:65]
	v_mfma_f32_16x16x32_bf16 v[58:61], v[168:171], v[192:195], v[58:61]
	v_mfma_f32_16x16x32_bf16 v[54:57], v[160:163], v[200:203], v[54:57]
	v_mfma_f32_16x16x32_bf16 v[46:49], v[168:171], v[200:203], v[46:49]
	v_mfma_f32_16x16x32_bf16 v[38:41], v[160:163], v[208:211], v[38:41]
	v_mfma_f32_16x16x32_bf16 v[30:33], v[168:171], v[208:211], v[30:33]
	v_mfma_f32_16x16x32_bf16 v[22:25], v[160:163], v[216:219], v[22:25]
	v_mfma_f32_16x16x32_bf16 v[14:17], v[168:171], v[216:219], v[14:17]
	s_nop 0
	s_nop 0
	v_mfma_f32_16x16x32_bf16 v[50:53], v[172:175], v[188:191], v[50:53]
	v_mfma_f32_16x16x32_bf16 v[42:45], v[180:183], v[188:191], v[42:45]
	v_mfma_f32_16x16x32_bf16 v[34:37], v[172:175], v[196:199], v[34:37]
	v_mfma_f32_16x16x32_bf16 v[26:29], v[180:183], v[196:199], v[26:29]
	v_mfma_f32_16x16x32_bf16 v[18:21], v[172:175], v[204:207], v[18:21]
	v_mfma_f32_16x16x32_bf16 v[10:13], v[180:183], v[204:207], v[10:13]
	v_mfma_f32_16x16x32_bf16 v[6:9], v[172:175], v[212:215], v[6:9]
	v_mfma_f32_16x16x32_bf16 v[2:5], v[180:183], v[212:215], v[2:5]
	v_mfma_f32_16x16x32_bf16 v[50:53], v[176:179], v[192:195], v[50:53]
	v_mfma_f32_16x16x32_bf16 v[42:45], v[184:187], v[192:195], v[42:45]
	v_mfma_f32_16x16x32_bf16 v[34:37], v[176:179], v[200:203], v[34:37]
	v_mfma_f32_16x16x32_bf16 v[26:29], v[184:187], v[200:203], v[26:29]
	v_mfma_f32_16x16x32_bf16 v[18:21], v[176:179], v[208:211], v[18:21]
	v_mfma_f32_16x16x32_bf16 v[10:13], v[184:187], v[208:211], v[10:13]
	v_mfma_f32_16x16x32_bf16 v[6:9], v[176:179], v[216:219], v[6:9]
	v_mfma_f32_16x16x32_bf16 v[2:5], v[184:187], v[216:219], v[2:5]
	s_nop 0
	s_barrier
	s_add_i32 s66, 0, 0x18000
	s_add_i32 s67, 0, 0x1c000
	v_add_u32_e32 v168, s66, v150
	v_add_u32_e32 v184, s67, v150
	ds_read_b128 v[156:159], v168
	ds_read_b128 v[160:163], v168 offset:1024
	ds_read_b128 v[164:167], v168 offset:2048
	ds_read_b128 v[168:171], v168 offset:3072
	ds_read_b128 v[172:175], v184
	ds_read_b128 v[176:179], v184 offset:1024
	ds_read_b128 v[180:183], v184 offset:2048
	ds_read_b128 v[184:187], v184 offset:3072
	s_add_u32 s38, s38, 0x80000
	s_addc_u32 s39, s39, 0
	s_mov_b32 m0, s47
	v_lshl_add_u64 v[228:229], s[38:39], 0, v[130:131]
	ds_read_b128 v[188:191], v155 offset:32768
	ds_read_b128 v[192:195], v155 offset:33792
	ds_read_b128 v[196:199], v155 offset:34816
	ds_read_b128 v[200:203], v155 offset:35840
	ds_read_b128 v[204:207], v155 offset:36864
	ds_read_b128 v[208:211], v155 offset:37888
	ds_read_b128 v[212:215], v155 offset:38912
	ds_read_b128 v[216:219], v155 offset:39936
	global_load_lds_dwordx4 v[228:229], off
	v_lshl_add_u64 v[228:229], s[38:39], 0, v[134:135]
	s_mov_b32 m0, s48
	s_nop 0
	global_load_lds_dwordx4 v[228:229], off
	s_waitcnt vmcnt(8)
	s_waitcnt lgkmcnt(0)
	s_barrier
	s_nop 0
	s_waitcnt lgkmcnt(0)
	v_mfma_f32_16x16x32_bf16 v[126:129], v[156:159], v[188:191], v[126:129]
	v_mfma_f32_16x16x32_bf16 v[122:125], v[164:167], v[188:191], v[122:125]
	v_mfma_f32_16x16x32_bf16 v[118:121], v[156:159], v[196:199], v[118:121]
	v_mfma_f32_16x16x32_bf16 v[110:113], v[164:167], v[196:199], v[110:113]
	v_mfma_f32_16x16x32_bf16 v[102:105], v[156:159], v[204:207], v[102:105]
	v_mfma_f32_16x16x32_bf16 v[94:97], v[164:167], v[204:207], v[94:97]
	v_mfma_f32_16x16x32_bf16 v[86:89], v[156:159], v[212:215], v[86:89]
	v_mfma_f32_16x16x32_bf16 v[78:81], v[164:167], v[212:215], v[78:81]
	v_mfma_f32_16x16x32_bf16 v[126:129], v[160:163], v[192:195], v[126:129]
	v_mfma_f32_16x16x32_bf16 v[122:125], v[168:171], v[192:195], v[122:125]
	v_mfma_f32_16x16x32_bf16 v[118:121], v[160:163], v[200:203], v[118:121]
	v_mfma_f32_16x16x32_bf16 v[110:113], v[168:171], v[200:203], v[110:113]
	v_mfma_f32_16x16x32_bf16 v[102:105], v[160:163], v[208:211], v[102:105]
	v_mfma_f32_16x16x32_bf16 v[94:97], v[168:171], v[208:211], v[94:97]
	v_mfma_f32_16x16x32_bf16 v[86:89], v[160:163], v[216:219], v[86:89]
	v_mfma_f32_16x16x32_bf16 v[78:81], v[168:171], v[216:219], v[78:81]
	s_nop 0
	s_nop 0
	v_mfma_f32_16x16x32_bf16 v[114:117], v[172:175], v[188:191], v[114:117]
	v_mfma_f32_16x16x32_bf16 v[106:109], v[180:183], v[188:191], v[106:109]
	v_mfma_f32_16x16x32_bf16 v[98:101], v[172:175], v[196:199], v[98:101]
	v_mfma_f32_16x16x32_bf16 v[90:93], v[180:183], v[196:199], v[90:93]
	v_mfma_f32_16x16x32_bf16 v[82:85], v[172:175], v[204:207], v[82:85]
	v_mfma_f32_16x16x32_bf16 v[74:77], v[180:183], v[204:207], v[74:77]
	v_mfma_f32_16x16x32_bf16 v[70:73], v[172:175], v[212:215], v[70:73]
	v_mfma_f32_16x16x32_bf16 v[66:69], v[180:183], v[212:215], v[66:69]
	v_mfma_f32_16x16x32_bf16 v[114:117], v[176:179], v[192:195], v[114:117]
	v_mfma_f32_16x16x32_bf16 v[106:109], v[184:187], v[192:195], v[106:109]
	v_mfma_f32_16x16x32_bf16 v[98:101], v[176:179], v[200:203], v[98:101]
	v_mfma_f32_16x16x32_bf16 v[90:93], v[184:187], v[200:203], v[90:93]
	v_mfma_f32_16x16x32_bf16 v[82:85], v[176:179], v[208:211], v[82:85]
	v_mfma_f32_16x16x32_bf16 v[74:77], v[184:187], v[208:211], v[74:77]
	v_mfma_f32_16x16x32_bf16 v[70:73], v[176:179], v[216:219], v[70:73]
	v_mfma_f32_16x16x32_bf16 v[66:69], v[184:187], v[216:219], v[66:69]
	s_nop 0
	s_barrier
	s_add_i32 s38, s66, s45
	v_lshl_add_u64 v[220:221], v[220:221], 0, s[8:9]
	s_mov_b32 m0, s38
	ds_read_b128 v[188:191], v155 offset:49152
	ds_read_b128 v[192:195], v155 offset:50176
	ds_read_b128 v[196:199], v155 offset:51200
	ds_read_b128 v[200:203], v155 offset:52224
	ds_read_b128 v[204:207], v155 offset:53248
	ds_read_b128 v[208:211], v155 offset:54272
	ds_read_b128 v[212:215], v155 offset:55296
	ds_read_b128 v[216:219], v155 offset:56320
	global_load_lds_dwordx4 v[220:221], off
	s_add_i32 m0, s38, 0x2000
	s_add_u32 s36, s36, 0x80080
	v_lshl_add_u64 v[220:221], v[222:223], 0, s[8:9]
	s_addc_u32 s37, s37, 0
	s_add_i32 s38, s67, s45
	global_load_lds_dwordx4 v[220:221], off
	v_lshl_add_u64 v[220:221], s[36:37], 0, v[132:133]
	s_mov_b32 m0, s38
	s_nop 0
	global_load_lds_dwordx4 v[220:221], off
	v_lshl_add_u64 v[220:221], s[36:37], 0, v[136:137]
	s_add_i32 m0, s38, 0x2000
	s_nop 0
	global_load_lds_dwordx4 v[220:221], off
	v_lshl_add_u64 v[220:221], v[224:225], 0, s[8:9]
	s_mov_b32 m0, s49
	s_nop 0
	global_load_lds_dwordx4 v[220:221], off
	v_lshl_add_u64 v[220:221], v[226:227], 0, s[8:9]
	s_mov_b32 m0, s50
	s_nop 0
	global_load_lds_dwordx4 v[220:221], off
	s_waitcnt vmcnt(8)
	s_waitcnt lgkmcnt(0)
	s_barrier
	s_nop 0
	s_waitcnt lgkmcnt(0)
	v_mfma_f32_16x16x32_bf16 v[62:65], v[156:159], v[188:191], v[62:65]
	v_mfma_f32_16x16x32_bf16 v[58:61], v[164:167], v[188:191], v[58:61]
	v_mfma_f32_16x16x32_bf16 v[54:57], v[156:159], v[196:199], v[54:57]
	v_mfma_f32_16x16x32_bf16 v[46:49], v[164:167], v[196:199], v[46:49]
	v_mfma_f32_16x16x32_bf16 v[38:41], v[156:159], v[204:207], v[38:41]
	v_mfma_f32_16x16x32_bf16 v[30:33], v[164:167], v[204:207], v[30:33]
	v_mfma_f32_16x16x32_bf16 v[22:25], v[156:159], v[212:215], v[22:25]
	v_mfma_f32_16x16x32_bf16 v[14:17], v[164:167], v[212:215], v[14:17]
	v_mfma_f32_16x16x32_bf16 v[62:65], v[160:163], v[192:195], v[62:65]
	v_mfma_f32_16x16x32_bf16 v[58:61], v[168:171], v[192:195], v[58:61]
	v_mfma_f32_16x16x32_bf16 v[54:57], v[160:163], v[200:203], v[54:57]
	v_mfma_f32_16x16x32_bf16 v[46:49], v[168:171], v[200:203], v[46:49]
	v_mfma_f32_16x16x32_bf16 v[38:41], v[160:163], v[208:211], v[38:41]
	v_mfma_f32_16x16x32_bf16 v[30:33], v[168:171], v[208:211], v[30:33]
	v_mfma_f32_16x16x32_bf16 v[22:25], v[160:163], v[216:219], v[22:25]
	v_mfma_f32_16x16x32_bf16 v[14:17], v[168:171], v[216:219], v[14:17]
	s_nop 0
	s_nop 0
	v_mfma_f32_16x16x32_bf16 v[50:53], v[172:175], v[188:191], v[50:53]
	v_mfma_f32_16x16x32_bf16 v[42:45], v[180:183], v[188:191], v[42:45]
	v_mfma_f32_16x16x32_bf16 v[34:37], v[172:175], v[196:199], v[34:37]
	v_mfma_f32_16x16x32_bf16 v[26:29], v[180:183], v[196:199], v[26:29]
	v_mfma_f32_16x16x32_bf16 v[18:21], v[172:175], v[204:207], v[18:21]
	v_mfma_f32_16x16x32_bf16 v[10:13], v[180:183], v[204:207], v[10:13]
	v_mfma_f32_16x16x32_bf16 v[6:9], v[172:175], v[212:215], v[6:9]
	v_mfma_f32_16x16x32_bf16 v[2:5], v[180:183], v[212:215], v[2:5]
	v_mfma_f32_16x16x32_bf16 v[50:53], v[176:179], v[192:195], v[50:53]
	v_mfma_f32_16x16x32_bf16 v[42:45], v[184:187], v[192:195], v[42:45]
	v_mfma_f32_16x16x32_bf16 v[34:37], v[176:179], v[200:203], v[34:37]
	v_mfma_f32_16x16x32_bf16 v[26:29], v[184:187], v[200:203], v[26:29]
	v_mfma_f32_16x16x32_bf16 v[18:21], v[176:179], v[208:211], v[18:21]
	v_mfma_f32_16x16x32_bf16 v[10:13], v[184:187], v[208:211], v[10:13]
	v_mfma_f32_16x16x32_bf16 v[6:9], v[176:179], v[216:219], v[6:9]
	v_mfma_f32_16x16x32_bf16 v[2:5], v[184:187], v[216:219], v[2:5]
	s_nop 0
	s_barrier
	s_add_i32 s65, s65, 2
	s_add_u32 s34, s34, 0x100
	s_addc_u32 s35, s35, 0
	s_cmp_gt_u32 s65, 29
	s_cbranch_scc0 .LBB0_1009
	s_setprio 0
	s_and_b64 vcc, exec, s[10:11]
	s_cbranch_vccz .LBB0_1012
	s_barrier

.LBB0_1172:
	s_ashr_i32 s13, s12, 31
	s_lshl_b64 s[14:15], s[12:13], 20
	s_add_u32 s14, s31, s14
	s_addc_u32 s15, s33, s15
	s_and_b64 s[16:17], s[4:5], exec
	s_cselect_b32 s13, s15, s21
	s_cselect_b32 s51, s14, s20
	s_ashr_i32 s11, s10, 31
	s_lshl_b64 s[16:17], s[10:11], 20
	s_add_u32 s16, s34, s16
	s_addc_u32 s17, s35, s17
	s_and_b64 s[26:27], s[4:5], exec
	s_cselect_b32 s11, s17, s25
	s_cselect_b32 s52, s16, s24
	s_cmp_lg_u32 s22, 0
	s_cselect_b64 s[22:23], -1, 0
	s_add_u32 s53, s24, 0x100
	v_mov_b32_e32 v2, 0
	s_addc_u32 s54, s25, 0
	v_lshl_add_u64 v[146:147], s[20:21], 0, v[138:139]
	v_lshl_add_u64 v[148:149], s[20:21], 0, v[140:141]
	s_mov_b32 s55, -2
	s_mov_b64 s[24:25], 0
	v_mov_b32_e32 v3, v2
	v_mov_b32_e32 v4, v2
	v_mov_b32_e32 v5, v2
	v_mov_b32_e32 v6, v2
	v_mov_b32_e32 v7, v2
	v_mov_b32_e32 v8, v2
	v_mov_b32_e32 v9, v2
	v_mov_b32_e32 v10, v2
	v_mov_b32_e32 v11, v2
	v_mov_b32_e32 v12, v2
	v_mov_b32_e32 v13, v2
	v_mov_b32_e32 v18, v2
	v_mov_b32_e32 v19, v2
	v_mov_b32_e32 v20, v2
	v_mov_b32_e32 v21, v2
	v_mov_b32_e32 v26, v2
	v_mov_b32_e32 v27, v2
	v_mov_b32_e32 v28, v2
	v_mov_b32_e32 v29, v2
	v_mov_b32_e32 v34, v2
	v_mov_b32_e32 v35, v2
	v_mov_b32_e32 v36, v2
	v_mov_b32_e32 v37, v2
	v_mov_b32_e32 v42, v2
	v_mov_b32_e32 v43, v2
	v_mov_b32_e32 v44, v2
	v_mov_b32_e32 v45, v2
	v_mov_b32_e32 v50, v2
	v_mov_b32_e32 v51, v2
	v_mov_b32_e32 v52, v2
	v_mov_b32_e32 v53, v2
	v_mov_b32_e32 v14, v2
	v_mov_b32_e32 v15, v2
	v_mov_b32_e32 v16, v2
	v_mov_b32_e32 v17, v2
	v_mov_b32_e32 v22, v2
	v_mov_b32_e32 v23, v2
	v_mov_b32_e32 v24, v2
	v_mov_b32_e32 v25, v2
	v_mov_b32_e32 v30, v2
	v_mov_b32_e32 v31, v2
	v_mov_b32_e32 v32, v2
	v_mov_b32_e32 v33, v2
	v_mov_b32_e32 v38, v2
	v_mov_b32_e32 v39, v2
	v_mov_b32_e32 v40, v2
	v_mov_b32_e32 v41, v2
	v_mov_b32_e32 v46, v2
	v_mov_b32_e32 v47, v2
	v_mov_b32_e32 v48, v2
	v_mov_b32_e32 v49, v2
	v_mov_b32_e32 v54, v2
	v_mov_b32_e32 v55, v2
	v_mov_b32_e32 v56, v2
	v_mov_b32_e32 v57, v2
	v_mov_b32_e32 v58, v2
	v_mov_b32_e32 v59, v2
	v_mov_b32_e32 v60, v2
	v_mov_b32_e32 v61, v2
	v_mov_b32_e32 v62, v2
	v_mov_b32_e32 v63, v2
	v_mov_b32_e32 v64, v2
	v_mov_b32_e32 v65, v2
	v_mov_b32_e32 v66, v2
	v_mov_b32_e32 v67, v2
	v_mov_b32_e32 v68, v2
	v_mov_b32_e32 v69, v2
	v_mov_b32_e32 v70, v2
	v_mov_b32_e32 v71, v2
	v_mov_b32_e32 v72, v2
	v_mov_b32_e32 v73, v2
	v_mov_b32_e32 v74, v2
	v_mov_b32_e32 v75, v2
	v_mov_b32_e32 v76, v2
	v_mov_b32_e32 v77, v2
	v_mov_b32_e32 v82, v2
	v_mov_b32_e32 v83, v2
	v_mov_b32_e32 v84, v2
	v_mov_b32_e32 v85, v2
	v_mov_b32_e32 v90, v2
	v_mov_b32_e32 v91, v2
	v_mov_b32_e32 v92, v2
	v_mov_b32_e32 v93, v2
	v_mov_b32_e32 v98, v2
	v_mov_b32_e32 v99, v2
	v_mov_b32_e32 v100, v2
	v_mov_b32_e32 v101, v2
	v_mov_b32_e32 v106, v2
	v_mov_b32_e32 v107, v2
	v_mov_b32_e32 v108, v2
	v_mov_b32_e32 v109, v2
	v_mov_b32_e32 v114, v2
	v_mov_b32_e32 v115, v2
	v_mov_b32_e32 v116, v2
	v_mov_b32_e32 v117, v2
	v_mov_b32_e32 v78, v2
	v_mov_b32_e32 v79, v2
	v_mov_b32_e32 v80, v2
	v_mov_b32_e32 v81, v2
	v_mov_b32_e32 v86, v2
	v_mov_b32_e32 v87, v2
	v_mov_b32_e32 v88, v2
	v_mov_b32_e32 v89, v2
	v_mov_b32_e32 v94, v2
	v_mov_b32_e32 v95, v2
	v_mov_b32_e32 v96, v2
	v_mov_b32_e32 v97, v2
	v_mov_b32_e32 v102, v2
	v_mov_b32_e32 v103, v2
	v_mov_b32_e32 v104, v2
	v_mov_b32_e32 v105, v2
	v_mov_b32_e32 v110, v2
	v_mov_b32_e32 v111, v2
	v_mov_b32_e32 v112, v2
	v_mov_b32_e32 v113, v2
	v_mov_b32_e32 v118, v2
	v_mov_b32_e32 v119, v2
	v_mov_b32_e32 v120, v2
	v_mov_b32_e32 v121, v2
	v_mov_b32_e32 v122, v2
	v_mov_b32_e32 v123, v2
	v_mov_b32_e32 v124, v2
	v_mov_b32_e32 v125, v2
	v_mov_b32_e32 v126, v2
	v_mov_b32_e32 v127, v2
	v_mov_b32_e32 v128, v2
	v_mov_b32_e32 v129, v2
	v_readfirstlane_b32 s98, v154
	s_lshr_b32 s98, s98, 8
	s_cmp_eq_u32 s98, 0
	s_cbranch_scc1 .Lgprio_4
	s_setprio 1
.Lgprio_4:
.LBB0_1173:
	ds_read_b128 v[156:159], v152
	ds_read_b128 v[160:163], v152 offset:1024
	ds_read_b128 v[164:167], v152 offset:2048
	ds_read_b128 v[168:171], v152 offset:3072
	ds_read_b128 v[172:175], v153
	ds_read_b128 v[176:179], v153 offset:1024
	ds_read_b128 v[180:183], v153 offset:2048
	ds_read_b128 v[184:187], v153 offset:3072
	s_add_u32 s26, s20, s24
	s_addc_u32 s27, s21, s25
	s_add_u32 s28, s26, 0x100
	s_addc_u32 s29, s27, 0
	s_add_u32 s56, s53, s24
	s_addc_u32 s57, s54, s25
	s_cmp_eq_u32 s24, 0
	s_cselect_b64 s[26:27], -1, 0
	s_and_b64 s[26:27], s[22:23], s[26:27]
	s_cmpk_eq_i32 s24, 0xf00
	v_cndmask_b32_e64 v188, 0, 1, s[26:27]
	s_cselect_b32 s29, s13, s29
	s_cselect_b32 s28, s51, s28
	v_readfirstlane_b32 s58, v188
	s_cselect_b32 s27, s11, s57
	s_cselect_b32 s26, s52, s56
	v_lshl_add_u64 v[220:221], v[148:149], 0, s[24:25]
	s_add_i32 m0, s19, 0xc000
	ds_read_b128 v[188:191], v155
	ds_read_b128 v[192:195], v155 offset:1024
	ds_read_b128 v[196:199], v155 offset:2048
	ds_read_b128 v[200:203], v155 offset:3072
	ds_read_b128 v[204:207], v155 offset:4096
	ds_read_b128 v[208:211], v155 offset:5120
	ds_read_b128 v[212:215], v155 offset:6144
	ds_read_b128 v[216:219], v155 offset:7168
	global_load_lds_dwordx4 v[220:221], off
	v_lshl_add_u64 v[220:221], v[146:147], 0, s[24:25]
	s_add_i32 m0, s19, 0xe000
	s_and_b32 s58, s58, 1
	global_load_lds_dwordx4 v[220:221], off
	s_cmp_eq_u32 s58, 0
	s_cbranch_scc1 .Lw8_8
	s_waitcnt vmcnt(24)
	s_branch .Lwe_8

.Lwe_8:
	s_waitcnt lgkmcnt(0)
	s_barrier
	s_nop 0
	s_waitcnt lgkmcnt(0)
	v_mfma_f32_16x16x32_bf16 v[126:129], v[156:159], v[188:191], v[126:129]
	v_mfma_f32_16x16x32_bf16 v[122:125], v[164:167], v[188:191], v[122:125]
	v_mfma_f32_16x16x32_bf16 v[118:121], v[156:159], v[196:199], v[118:121]
	v_mfma_f32_16x16x32_bf16 v[110:113], v[164:167], v[196:199], v[110:113]
	v_mfma_f32_16x16x32_bf16 v[102:105], v[156:159], v[204:207], v[102:105]
	v_mfma_f32_16x16x32_bf16 v[94:97], v[164:167], v[204:207], v[94:97]
	v_mfma_f32_16x16x32_bf16 v[86:89], v[156:159], v[212:215], v[86:89]
	v_mfma_f32_16x16x32_bf16 v[78:81], v[164:167], v[212:215], v[78:81]
	v_mfma_f32_16x16x32_bf16 v[126:129], v[160:163], v[192:195], v[126:129]
	v_mfma_f32_16x16x32_bf16 v[122:125], v[168:171], v[192:195], v[122:125]
	v_mfma_f32_16x16x32_bf16 v[118:121], v[160:163], v[200:203], v[118:121]
	v_mfma_f32_16x16x32_bf16 v[110:113], v[168:171], v[200:203], v[110:113]
	v_mfma_f32_16x16x32_bf16 v[102:105], v[160:163], v[208:211], v[102:105]
	v_mfma_f32_16x16x32_bf16 v[94:97], v[168:171], v[208:211], v[94:97]
	v_mfma_f32_16x16x32_bf16 v[86:89], v[160:163], v[216:219], v[86:89]
	v_mfma_f32_16x16x32_bf16 v[78:81], v[168:171], v[216:219], v[78:81]
	s_nop 0
	s_nop 0
	v_mfma_f32_16x16x32_bf16 v[114:117], v[172:175], v[188:191], v[114:117]
	v_mfma_f32_16x16x32_bf16 v[106:109], v[180:183], v[188:191], v[106:109]
	v_mfma_f32_16x16x32_bf16 v[98:101], v[172:175], v[196:199], v[98:101]
	v_mfma_f32_16x16x32_bf16 v[90:93], v[180:183], v[196:199], v[90:93]
	v_mfma_f32_16x16x32_bf16 v[82:85], v[172:175], v[204:207], v[82:85]
	v_mfma_f32_16x16x32_bf16 v[74:77], v[180:183], v[204:207], v[74:77]
	v_mfma_f32_16x16x32_bf16 v[70:73], v[172:175], v[212:215], v[70:73]
	v_mfma_f32_16x16x32_bf16 v[66:69], v[180:183], v[212:215], v[66:69]
	v_mfma_f32_16x16x32_bf16 v[114:117], v[176:179], v[192:195], v[114:117]
	v_mfma_f32_16x16x32_bf16 v[106:109], v[184:187], v[192:195], v[106:109]
	v_mfma_f32_16x16x32_bf16 v[98:101], v[176:179], v[200:203], v[98:101]
	v_mfma_f32_16x16x32_bf16 v[90:93], v[184:187], v[200:203], v[90:93]
	v_mfma_f32_16x16x32_bf16 v[82:85], v[176:179], v[208:211], v[82:85]
	v_mfma_f32_16x16x32_bf16 v[74:77], v[184:187], v[208:211], v[74:77]
	v_mfma_f32_16x16x32_bf16 v[70:73], v[176:179], v[216:219], v[70:73]
	v_mfma_f32_16x16x32_bf16 v[66:69], v[184:187], v[216:219], v[66:69]
	s_nop 0
	s_barrier
	s_add_i32 s56, s46, s36
	v_lshl_add_u64 v[220:221], s[26:27], 0, v[134:135]
	s_mov_b32 m0, s56
	ds_read_b128 v[188:191], v155 offset:16384
	ds_read_b128 v[192:195], v155 offset:17408
	ds_read_b128 v[196:199], v155 offset:18432
	ds_read_b128 v[200:203], v155 offset:19456
	ds_read_b128 v[204:207], v155 offset:20480
	ds_read_b128 v[208:211], v155 offset:21504
	ds_read_b128 v[212:215], v155 offset:22528
	ds_read_b128 v[216:219], v155 offset:23552
	global_load_lds_dwordx4 v[220:221], off
	s_add_i32 m0, s56, 0x2000
	s_add_u32 s56, s26, 0x80000
	v_lshl_add_u64 v[222:223], s[26:27], 0, v[130:131]
	s_addc_u32 s57, s27, 0
	s_add_i32 s59, s47, s36
	global_load_lds_dwordx4 v[222:223], off
	v_lshl_add_u64 v[224:225], s[56:57], 0, v[134:135]
	s_mov_b32 m0, s59
	v_lshl_add_u64 v[226:227], s[28:29], 0, v[132:133]
	global_load_lds_dwordx4 v[224:225], off
	v_lshl_add_u64 v[224:225], s[56:57], 0, v[130:131]
	s_add_i32 m0, s59, 0x2000
	s_nop 0
	global_load_lds_dwordx4 v[224:225], off
	v_lshl_add_u64 v[224:225], s[28:29], 0, v[136:137]
	s_mov_b32 m0, s19
	s_nop 0
	global_load_lds_dwordx4 v[224:225], off
	s_mov_b32 m0, s39
	s_nop 0
	global_load_lds_dwordx4 v[226:227], off
	s_cmp_eq_u32 s58, 0
	s_cbranch_scc1 .Lw8_9
	s_waitcnt vmcnt(24)
	s_branch .Lwe_9

.Lwe_9:
	s_waitcnt lgkmcnt(0)
	s_barrier
	s_nop 0
	s_waitcnt lgkmcnt(0)
	v_mfma_f32_16x16x32_bf16 v[62:65], v[156:159], v[188:191], v[62:65]
	v_mfma_f32_16x16x32_bf16 v[58:61], v[164:167], v[188:191], v[58:61]
	v_mfma_f32_16x16x32_bf16 v[54:57], v[156:159], v[196:199], v[54:57]
	v_mfma_f32_16x16x32_bf16 v[46:49], v[164:167], v[196:199], v[46:49]
	v_mfma_f32_16x16x32_bf16 v[38:41], v[156:159], v[204:207], v[38:41]
	v_mfma_f32_16x16x32_bf16 v[30:33], v[164:167], v[204:207], v[30:33]
	v_mfma_f32_16x16x32_bf16 v[22:25], v[156:159], v[212:215], v[22:25]
	v_mfma_f32_16x16x32_bf16 v[14:17], v[164:167], v[212:215], v[14:17]
	v_mfma_f32_16x16x32_bf16 v[62:65], v[160:163], v[192:195], v[62:65]
	v_mfma_f32_16x16x32_bf16 v[58:61], v[168:171], v[192:195], v[58:61]
	v_mfma_f32_16x16x32_bf16 v[54:57], v[160:163], v[200:203], v[54:57]
	v_mfma_f32_16x16x32_bf16 v[46:49], v[168:171], v[200:203], v[46:49]
	v_mfma_f32_16x16x32_bf16 v[38:41], v[160:163], v[208:211], v[38:41]
	v_mfma_f32_16x16x32_bf16 v[30:33], v[168:171], v[208:211], v[30:33]
	v_mfma_f32_16x16x32_bf16 v[22:25], v[160:163], v[216:219], v[22:25]
	v_mfma_f32_16x16x32_bf16 v[14:17], v[168:171], v[216:219], v[14:17]
	s_nop 0
	s_nop 0
	v_mfma_f32_16x16x32_bf16 v[50:53], v[172:175], v[188:191], v[50:53]
	v_mfma_f32_16x16x32_bf16 v[42:45], v[180:183], v[188:191], v[42:45]
	v_mfma_f32_16x16x32_bf16 v[34:37], v[172:175], v[196:199], v[34:37]
	v_mfma_f32_16x16x32_bf16 v[26:29], v[180:183], v[196:199], v[26:29]
	v_mfma_f32_16x16x32_bf16 v[18:21], v[172:175], v[204:207], v[18:21]
	v_mfma_f32_16x16x32_bf16 v[10:13], v[180:183], v[204:207], v[10:13]
	v_mfma_f32_16x16x32_bf16 v[6:9], v[172:175], v[212:215], v[6:9]
	v_mfma_f32_16x16x32_bf16 v[2:5], v[180:183], v[212:215], v[2:5]
	v_mfma_f32_16x16x32_bf16 v[50:53], v[176:179], v[192:195], v[50:53]
	v_mfma_f32_16x16x32_bf16 v[42:45], v[184:187], v[192:195], v[42:45]
	v_mfma_f32_16x16x32_bf16 v[34:37], v[176:179], v[200:203], v[34:37]
	v_mfma_f32_16x16x32_bf16 v[26:29], v[184:187], v[200:203], v[26:29]
	v_mfma_f32_16x16x32_bf16 v[18:21], v[176:179], v[208:211], v[18:21]
	v_mfma_f32_16x16x32_bf16 v[10:13], v[184:187], v[208:211], v[10:13]
	v_mfma_f32_16x16x32_bf16 v[6:9], v[176:179], v[216:219], v[6:9]
	v_mfma_f32_16x16x32_bf16 v[2:5], v[184:187], v[216:219], v[2:5]
	s_nop 0
	s_barrier
	s_add_i32 s56, 0, 0x18000
	s_add_i32 s57, 0, 0x1c000
	v_add_u32_e32 v168, s56, v150
	v_add_u32_e32 v184, s57, v150
	ds_read_b128 v[156:159], v168
	ds_read_b128 v[160:163], v168 offset:1024
	ds_read_b128 v[164:167], v168 offset:2048
	ds_read_b128 v[168:171], v168 offset:3072
	ds_read_b128 v[172:175], v184
	ds_read_b128 v[176:179], v184 offset:1024
	ds_read_b128 v[180:183], v184 offset:2048
	ds_read_b128 v[184:187], v184 offset:3072
	s_add_u32 s28, s28, 0x80000
	s_addc_u32 s29, s29, 0
	s_mov_b32 m0, s40
	v_lshl_add_u64 v[228:229], s[28:29], 0, v[136:137]
	ds_read_b128 v[188:191], v155 offset:32768
	ds_read_b128 v[192:195], v155 offset:33792
	ds_read_b128 v[196:199], v155 offset:34816
	ds_read_b128 v[200:203], v155 offset:35840
	ds_read_b128 v[204:207], v155 offset:36864
	ds_read_b128 v[208:211], v155 offset:37888
	ds_read_b128 v[212:215], v155 offset:38912
	ds_read_b128 v[216:219], v155 offset:39936
	global_load_lds_dwordx4 v[228:229], off
	v_lshl_add_u64 v[228:229], s[28:29], 0, v[132:133]
	s_mov_b32 m0, s41
	s_nop 0
	global_load_lds_dwordx4 v[228:229], off
	s_waitcnt vmcnt(8)
	s_waitcnt lgkmcnt(0)
	s_barrier
	s_nop 0
	s_waitcnt lgkmcnt(0)
	v_mfma_f32_16x16x32_bf16 v[126:129], v[156:159], v[188:191], v[126:129]
	v_mfma_f32_16x16x32_bf16 v[122:125], v[164:167], v[188:191], v[122:125]
	v_mfma_f32_16x16x32_bf16 v[118:121], v[156:159], v[196:199], v[118:121]
	v_mfma_f32_16x16x32_bf16 v[110:113], v[164:167], v[196:199], v[110:113]
	v_mfma_f32_16x16x32_bf16 v[102:105], v[156:159], v[204:207], v[102:105]
	v_mfma_f32_16x16x32_bf16 v[94:97], v[164:167], v[204:207], v[94:97]
	v_mfma_f32_16x16x32_bf16 v[86:89], v[156:159], v[212:215], v[86:89]
	v_mfma_f32_16x16x32_bf16 v[78:81], v[164:167], v[212:215], v[78:81]
	v_mfma_f32_16x16x32_bf16 v[126:129], v[160:163], v[192:195], v[126:129]
	v_mfma_f32_16x16x32_bf16 v[122:125], v[168:171], v[192:195], v[122:125]
	v_mfma_f32_16x16x32_bf16 v[118:121], v[160:163], v[200:203], v[118:121]
	v_mfma_f32_16x16x32_bf16 v[110:113], v[168:171], v[200:203], v[110:113]
	v_mfma_f32_16x16x32_bf16 v[102:105], v[160:163], v[208:211], v[102:105]
	v_mfma_f32_16x16x32_bf16 v[94:97], v[168:171], v[208:211], v[94:97]
	v_mfma_f32_16x16x32_bf16 v[86:89], v[160:163], v[216:219], v[86:89]
	v_mfma_f32_16x16x32_bf16 v[78:81], v[168:171], v[216:219], v[78:81]
	s_nop 0
	s_nop 0
	v_mfma_f32_16x16x32_bf16 v[114:117], v[172:175], v[188:191], v[114:117]
	v_mfma_f32_16x16x32_bf16 v[106:109], v[180:183], v[188:191], v[106:109]
	v_mfma_f32_16x16x32_bf16 v[98:101], v[172:175], v[196:199], v[98:101]
	v_mfma_f32_16x16x32_bf16 v[90:93], v[180:183], v[196:199], v[90:93]
	v_mfma_f32_16x16x32_bf16 v[82:85], v[172:175], v[204:207], v[82:85]
	v_mfma_f32_16x16x32_bf16 v[74:77], v[180:183], v[204:207], v[74:77]
	v_mfma_f32_16x16x32_bf16 v[70:73], v[172:175], v[212:215], v[70:73]
	v_mfma_f32_16x16x32_bf16 v[66:69], v[180:183], v[212:215], v[66:69]
	v_mfma_f32_16x16x32_bf16 v[114:117], v[176:179], v[192:195], v[114:117]
	v_mfma_f32_16x16x32_bf16 v[106:109], v[184:187], v[192:195], v[106:109]
	v_mfma_f32_16x16x32_bf16 v[98:101], v[176:179], v[200:203], v[98:101]
	v_mfma_f32_16x16x32_bf16 v[90:93], v[184:187], v[200:203], v[90:93]
	v_mfma_f32_16x16x32_bf16 v[82:85], v[176:179], v[208:211], v[82:85]
	v_mfma_f32_16x16x32_bf16 v[74:77], v[184:187], v[208:211], v[74:77]
	v_mfma_f32_16x16x32_bf16 v[70:73], v[176:179], v[216:219], v[70:73]
	v_mfma_f32_16x16x32_bf16 v[66:69], v[184:187], v[216:219], v[66:69]
	s_nop 0
	s_barrier
	s_add_i32 s28, s56, s36
	v_lshl_add_u64 v[220:221], v[220:221], 0, s[6:7]
	s_mov_b32 m0, s28
	ds_read_b128 v[188:191], v155 offset:49152
	ds_read_b128 v[192:195], v155 offset:50176
	ds_read_b128 v[196:199], v155 offset:51200
	ds_read_b128 v[200:203], v155 offset:52224
	ds_read_b128 v[204:207], v155 offset:53248
	ds_read_b128 v[208:211], v155 offset:54272
	ds_read_b128 v[212:215], v155 offset:55296
	ds_read_b128 v[216:219], v155 offset:56320
	global_load_lds_dwordx4 v[220:221], off
	s_add_i32 m0, s28, 0x2000
	s_add_u32 s26, s26, 0x80080
	v_lshl_add_u64 v[220:221], v[222:223], 0, s[6:7]
	s_addc_u32 s27, s27, 0
	s_add_i32 s28, s57, s36
	global_load_lds_dwordx4 v[220:221], off
	v_lshl_add_u64 v[220:221], s[26:27], 0, v[134:135]
	s_mov_b32 m0, s28
	s_nop 0
	global_load_lds_dwordx4 v[220:221], off
	v_lshl_add_u64 v[220:221], s[26:27], 0, v[130:131]
	s_add_i32 m0, s28, 0x2000
	s_nop 0
	global_load_lds_dwordx4 v[220:221], off
	v_lshl_add_u64 v[220:221], v[224:225], 0, s[6:7]
	s_mov_b32 m0, s42
	s_nop 0
	global_load_lds_dwordx4 v[220:221], off
	v_lshl_add_u64 v[220:221], v[226:227], 0, s[6:7]
	s_mov_b32 m0, s43
	s_nop 0
	global_load_lds_dwordx4 v[220:221], off
	s_waitcnt vmcnt(8)
	s_waitcnt lgkmcnt(0)
	s_barrier
	s_nop 0
	s_waitcnt lgkmcnt(0)
	v_mfma_f32_16x16x32_bf16 v[62:65], v[156:159], v[188:191], v[62:65]
	v_mfma_f32_16x16x32_bf16 v[58:61], v[164:167], v[188:191], v[58:61]
	v_mfma_f32_16x16x32_bf16 v[54:57], v[156:159], v[196:199], v[54:57]
	v_mfma_f32_16x16x32_bf16 v[46:49], v[164:167], v[196:199], v[46:49]
	v_mfma_f32_16x16x32_bf16 v[38:41], v[156:159], v[204:207], v[38:41]
	v_mfma_f32_16x16x32_bf16 v[30:33], v[164:167], v[204:207], v[30:33]
	v_mfma_f32_16x16x32_bf16 v[22:25], v[156:159], v[212:215], v[22:25]
	v_mfma_f32_16x16x32_bf16 v[14:17], v[164:167], v[212:215], v[14:17]
	v_mfma_f32_16x16x32_bf16 v[62:65], v[160:163], v[192:195], v[62:65]
	v_mfma_f32_16x16x32_bf16 v[58:61], v[168:171], v[192:195], v[58:61]
	v_mfma_f32_16x16x32_bf16 v[54:57], v[160:163], v[200:203], v[54:57]
	v_mfma_f32_16x16x32_bf16 v[46:49], v[168:171], v[200:203], v[46:49]
	v_mfma_f32_16x16x32_bf16 v[38:41], v[160:163], v[208:211], v[38:41]
	v_mfma_f32_16x16x32_bf16 v[30:33], v[168:171], v[208:211], v[30:33]
	v_mfma_f32_16x16x32_bf16 v[22:25], v[160:163], v[216:219], v[22:25]
	v_mfma_f32_16x16x32_bf16 v[14:17], v[168:171], v[216:219], v[14:17]
	s_nop 0
	s_nop 0
	v_mfma_f32_16x16x32_bf16 v[50:53], v[172:175], v[188:191], v[50:53]
	v_mfma_f32_16x16x32_bf16 v[42:45], v[180:183], v[188:191], v[42:45]
	v_mfma_f32_16x16x32_bf16 v[34:37], v[172:175], v[196:199], v[34:37]
	v_mfma_f32_16x16x32_bf16 v[26:29], v[180:183], v[196:199], v[26:29]
	v_mfma_f32_16x16x32_bf16 v[18:21], v[172:175], v[204:207], v[18:21]
	v_mfma_f32_16x16x32_bf16 v[10:13], v[180:183], v[204:207], v[10:13]
	v_mfma_f32_16x16x32_bf16 v[6:9], v[172:175], v[212:215], v[6:9]
	v_mfma_f32_16x16x32_bf16 v[2:5], v[180:183], v[212:215], v[2:5]
	v_mfma_f32_16x16x32_bf16 v[50:53], v[176:179], v[192:195], v[50:53]
	v_mfma_f32_16x16x32_bf16 v[42:45], v[184:187], v[192:195], v[42:45]
	v_mfma_f32_16x16x32_bf16 v[34:37], v[176:179], v[200:203], v[34:37]
	v_mfma_f32_16x16x32_bf16 v[26:29], v[184:187], v[200:203], v[26:29]
	v_mfma_f32_16x16x32_bf16 v[18:21], v[176:179], v[208:211], v[18:21]
	v_mfma_f32_16x16x32_bf16 v[10:13], v[184:187], v[208:211], v[10:13]
	v_mfma_f32_16x16x32_bf16 v[6:9], v[176:179], v[216:219], v[6:9]
	v_mfma_f32_16x16x32_bf16 v[2:5], v[184:187], v[216:219], v[2:5]
	s_nop 0
	s_barrier
	s_add_i32 s55, s55, 2
	s_add_u32 s24, s24, 0x100
	s_addc_u32 s25, s25, 0
	s_cmp_gt_u32 s55, 29
	s_cbranch_scc0 .LBB0_1173
	s_setprio 0
	s_and_b64 vcc, exec, s[8:9]
	s_cbranch_vccz .LBB0_1176
	s_barrier

.LBB0_1416:
	s_cmp_lg_u32 s24, 0
	s_cselect_b64 s[24:25], -1, 0
	s_add_u32 s59, s26, 0x100
	v_mov_b32_e32 v2, 0
	s_addc_u32 s60, s27, 0
	v_lshl_add_u64 v[146:147], s[22:23], 0, v[138:139]
	v_lshl_add_u64 v[148:149], s[22:23], 0, v[140:141]
	s_mov_b32 s61, -2
	s_mov_b64 s[26:27], 0
	v_mov_b32_e32 v3, v2
	v_mov_b32_e32 v4, v2
	v_mov_b32_e32 v5, v2
	v_mov_b32_e32 v6, v2
	v_mov_b32_e32 v7, v2
	v_mov_b32_e32 v8, v2
	v_mov_b32_e32 v9, v2
	v_mov_b32_e32 v10, v2
	v_mov_b32_e32 v11, v2
	v_mov_b32_e32 v12, v2
	v_mov_b32_e32 v13, v2
	v_mov_b32_e32 v18, v2
	v_mov_b32_e32 v19, v2
	v_mov_b32_e32 v20, v2
	v_mov_b32_e32 v21, v2
	v_mov_b32_e32 v26, v2
	v_mov_b32_e32 v27, v2
	v_mov_b32_e32 v28, v2
	v_mov_b32_e32 v29, v2
	v_mov_b32_e32 v34, v2
	v_mov_b32_e32 v35, v2
	v_mov_b32_e32 v36, v2
	v_mov_b32_e32 v37, v2
	v_mov_b32_e32 v42, v2
	v_mov_b32_e32 v43, v2
	v_mov_b32_e32 v44, v2
	v_mov_b32_e32 v45, v2
	v_mov_b32_e32 v50, v2
	v_mov_b32_e32 v51, v2
	v_mov_b32_e32 v52, v2
	v_mov_b32_e32 v53, v2
	v_mov_b32_e32 v14, v2
	v_mov_b32_e32 v15, v2
	v_mov_b32_e32 v16, v2
	v_mov_b32_e32 v17, v2
	v_mov_b32_e32 v22, v2
	v_mov_b32_e32 v23, v2
	v_mov_b32_e32 v24, v2
	v_mov_b32_e32 v25, v2
	v_mov_b32_e32 v30, v2
	v_mov_b32_e32 v31, v2
	v_mov_b32_e32 v32, v2
	v_mov_b32_e32 v33, v2
	v_mov_b32_e32 v38, v2
	v_mov_b32_e32 v39, v2
	v_mov_b32_e32 v40, v2
	v_mov_b32_e32 v41, v2
	v_mov_b32_e32 v46, v2
	v_mov_b32_e32 v47, v2
	v_mov_b32_e32 v48, v2
	v_mov_b32_e32 v49, v2
	v_mov_b32_e32 v54, v2
	v_mov_b32_e32 v55, v2
	v_mov_b32_e32 v56, v2
	v_mov_b32_e32 v57, v2
	v_mov_b32_e32 v58, v2
	v_mov_b32_e32 v59, v2
	v_mov_b32_e32 v60, v2
	v_mov_b32_e32 v61, v2
	v_mov_b32_e32 v62, v2
	v_mov_b32_e32 v63, v2
	v_mov_b32_e32 v64, v2
	v_mov_b32_e32 v65, v2
	v_mov_b32_e32 v66, v2
	v_mov_b32_e32 v67, v2
	v_mov_b32_e32 v68, v2
	v_mov_b32_e32 v69, v2
	v_mov_b32_e32 v70, v2
	v_mov_b32_e32 v71, v2
	v_mov_b32_e32 v72, v2
	v_mov_b32_e32 v73, v2
	v_mov_b32_e32 v74, v2
	v_mov_b32_e32 v75, v2
	v_mov_b32_e32 v76, v2
	v_mov_b32_e32 v77, v2
	v_mov_b32_e32 v82, v2
	v_mov_b32_e32 v83, v2
	v_mov_b32_e32 v84, v2
	v_mov_b32_e32 v85, v2
	v_mov_b32_e32 v90, v2
	v_mov_b32_e32 v91, v2
	v_mov_b32_e32 v92, v2
	v_mov_b32_e32 v93, v2
	v_mov_b32_e32 v98, v2
	v_mov_b32_e32 v99, v2
	v_mov_b32_e32 v100, v2
	v_mov_b32_e32 v101, v2
	v_mov_b32_e32 v106, v2
	v_mov_b32_e32 v107, v2
	v_mov_b32_e32 v108, v2
	v_mov_b32_e32 v109, v2
	v_mov_b32_e32 v114, v2
	v_mov_b32_e32 v115, v2
	v_mov_b32_e32 v116, v2
	v_mov_b32_e32 v117, v2
	v_mov_b32_e32 v78, v2
	v_mov_b32_e32 v79, v2
	v_mov_b32_e32 v80, v2
	v_mov_b32_e32 v81, v2
	v_mov_b32_e32 v86, v2
	v_mov_b32_e32 v87, v2
	v_mov_b32_e32 v88, v2
	v_mov_b32_e32 v89, v2
	v_mov_b32_e32 v94, v2
	v_mov_b32_e32 v95, v2
	v_mov_b32_e32 v96, v2
	v_mov_b32_e32 v97, v2
	v_mov_b32_e32 v102, v2
	v_mov_b32_e32 v103, v2
	v_mov_b32_e32 v104, v2
	v_mov_b32_e32 v105, v2
	v_mov_b32_e32 v110, v2
	v_mov_b32_e32 v111, v2
	v_mov_b32_e32 v112, v2
	v_mov_b32_e32 v113, v2
	v_mov_b32_e32 v118, v2
	v_mov_b32_e32 v119, v2
	v_mov_b32_e32 v120, v2
	v_mov_b32_e32 v121, v2
	v_mov_b32_e32 v122, v2
	v_mov_b32_e32 v123, v2
	v_mov_b32_e32 v124, v2
	v_mov_b32_e32 v125, v2
	v_mov_b32_e32 v126, v2
	v_mov_b32_e32 v127, v2
	v_mov_b32_e32 v128, v2
	v_mov_b32_e32 v129, v2
	v_readfirstlane_b32 s98, v154
	s_lshr_b32 s98, s98, 8
	s_cmp_eq_u32 s98, 0
	s_cbranch_scc1 .Lgprio_5
	s_setprio 1
.Lgprio_5:
.LBB0_1417:
	ds_read_b128 v[156:159], v152
	ds_read_b128 v[160:163], v152 offset:1024
	ds_read_b128 v[164:167], v152 offset:2048
	ds_read_b128 v[168:171], v152 offset:3072
	ds_read_b128 v[172:175], v153
	ds_read_b128 v[176:179], v153 offset:1024
	ds_read_b128 v[180:183], v153 offset:2048
	ds_read_b128 v[184:187], v153 offset:3072
	s_add_u32 s28, s22, s26
	s_addc_u32 s29, s23, s27
	s_add_u32 s30, s28, 0x100
	s_addc_u32 s31, s29, 0
	s_add_u32 s62, s59, s26
	s_addc_u32 s63, s60, s27
	s_cmp_eq_u32 s26, 0
	s_cselect_b64 s[28:29], -1, 0
	s_and_b64 s[28:29], s[24:25], s[28:29]
	s_cmpk_eq_i32 s26, 0x2b00
	v_cndmask_b32_e64 v188, 0, 1, s[28:29]
	s_cselect_b32 s31, s7, s31
	s_cselect_b32 s30, s6, s30
	v_readfirstlane_b32 s64, v188
	s_cselect_b32 s29, s21, s63
	s_cselect_b32 s28, s20, s62
	v_lshl_add_u64 v[220:221], v[148:149], 0, s[26:27]
	s_add_i32 m0, s40, 0xc000
	ds_read_b128 v[188:191], v155
	ds_read_b128 v[192:195], v155 offset:1024
	ds_read_b128 v[196:199], v155 offset:2048
	ds_read_b128 v[200:203], v155 offset:3072
	ds_read_b128 v[204:207], v155 offset:4096
	ds_read_b128 v[208:211], v155 offset:5120
	ds_read_b128 v[212:215], v155 offset:6144
	ds_read_b128 v[216:219], v155 offset:7168
	global_load_lds_dwordx4 v[220:221], off
	v_lshl_add_u64 v[220:221], v[146:147], 0, s[26:27]
	s_add_i32 m0, s40, 0xe000
	s_and_b32 s64, s64, 1
	global_load_lds_dwordx4 v[220:221], off
	s_cmp_eq_u32 s64, 0
	s_cbranch_scc1 .Lw8_10
	s_waitcnt vmcnt(24)
	s_branch .Lwe_10

.Lwe_10:
	s_waitcnt lgkmcnt(0)
	s_barrier
	s_nop 0
	s_waitcnt lgkmcnt(0)
	v_mfma_f32_16x16x32_bf16 v[126:129], v[156:159], v[188:191], v[126:129]
	v_mfma_f32_16x16x32_bf16 v[122:125], v[164:167], v[188:191], v[122:125]
	v_mfma_f32_16x16x32_bf16 v[118:121], v[156:159], v[196:199], v[118:121]
	v_mfma_f32_16x16x32_bf16 v[110:113], v[164:167], v[196:199], v[110:113]
	v_mfma_f32_16x16x32_bf16 v[102:105], v[156:159], v[204:207], v[102:105]
	v_mfma_f32_16x16x32_bf16 v[94:97], v[164:167], v[204:207], v[94:97]
	v_mfma_f32_16x16x32_bf16 v[86:89], v[156:159], v[212:215], v[86:89]
	v_mfma_f32_16x16x32_bf16 v[78:81], v[164:167], v[212:215], v[78:81]
	v_mfma_f32_16x16x32_bf16 v[126:129], v[160:163], v[192:195], v[126:129]
	v_mfma_f32_16x16x32_bf16 v[122:125], v[168:171], v[192:195], v[122:125]
	v_mfma_f32_16x16x32_bf16 v[118:121], v[160:163], v[200:203], v[118:121]
	v_mfma_f32_16x16x32_bf16 v[110:113], v[168:171], v[200:203], v[110:113]
	v_mfma_f32_16x16x32_bf16 v[102:105], v[160:163], v[208:211], v[102:105]
	v_mfma_f32_16x16x32_bf16 v[94:97], v[168:171], v[208:211], v[94:97]
	v_mfma_f32_16x16x32_bf16 v[86:89], v[160:163], v[216:219], v[86:89]
	v_mfma_f32_16x16x32_bf16 v[78:81], v[168:171], v[216:219], v[78:81]
	s_nop 0
	s_nop 0
	v_mfma_f32_16x16x32_bf16 v[114:117], v[172:175], v[188:191], v[114:117]
	v_mfma_f32_16x16x32_bf16 v[106:109], v[180:183], v[188:191], v[106:109]
	v_mfma_f32_16x16x32_bf16 v[98:101], v[172:175], v[196:199], v[98:101]
	v_mfma_f32_16x16x32_bf16 v[90:93], v[180:183], v[196:199], v[90:93]
	v_mfma_f32_16x16x32_bf16 v[82:85], v[172:175], v[204:207], v[82:85]
	v_mfma_f32_16x16x32_bf16 v[74:77], v[180:183], v[204:207], v[74:77]
	v_mfma_f32_16x16x32_bf16 v[70:73], v[172:175], v[212:215], v[70:73]
	v_mfma_f32_16x16x32_bf16 v[66:69], v[180:183], v[212:215], v[66:69]
	v_mfma_f32_16x16x32_bf16 v[114:117], v[176:179], v[192:195], v[114:117]
	v_mfma_f32_16x16x32_bf16 v[106:109], v[184:187], v[192:195], v[106:109]
	v_mfma_f32_16x16x32_bf16 v[98:101], v[176:179], v[200:203], v[98:101]
	v_mfma_f32_16x16x32_bf16 v[90:93], v[184:187], v[200:203], v[90:93]
	v_mfma_f32_16x16x32_bf16 v[82:85], v[176:179], v[208:211], v[82:85]
	v_mfma_f32_16x16x32_bf16 v[74:77], v[184:187], v[208:211], v[74:77]
	v_mfma_f32_16x16x32_bf16 v[70:73], v[176:179], v[216:219], v[70:73]
	v_mfma_f32_16x16x32_bf16 v[66:69], v[184:187], v[216:219], v[66:69]
	s_nop 0
	s_barrier
	s_add_i32 s62, s48, s39
	v_lshl_add_u64 v[220:221], s[28:29], 0, v[132:133]
	s_mov_b32 m0, s62
	ds_read_b128 v[188:191], v155 offset:16384
	ds_read_b128 v[192:195], v155 offset:17408
	ds_read_b128 v[196:199], v155 offset:18432
	ds_read_b128 v[200:203], v155 offset:19456
	ds_read_b128 v[204:207], v155 offset:20480
	ds_read_b128 v[208:211], v155 offset:21504
	ds_read_b128 v[212:215], v155 offset:22528
	ds_read_b128 v[216:219], v155 offset:23552
	global_load_lds_dwordx4 v[220:221], off
	s_add_i32 m0, s62, 0x2000
	s_add_u32 s62, s28, 0x160000
	v_lshl_add_u64 v[222:223], s[28:29], 0, v[136:137]
	s_addc_u32 s63, s29, 0
	s_add_i32 s65, s49, s39
	global_load_lds_dwordx4 v[222:223], off
	v_lshl_add_u64 v[224:225], s[62:63], 0, v[132:133]
	s_mov_b32 m0, s65
	v_lshl_add_u64 v[226:227], s[30:31], 0, v[134:135]
	global_load_lds_dwordx4 v[224:225], off
	v_lshl_add_u64 v[224:225], s[62:63], 0, v[136:137]
	s_add_i32 m0, s65, 0x2000
	s_nop 0
	global_load_lds_dwordx4 v[224:225], off
	v_lshl_add_u64 v[224:225], s[30:31], 0, v[130:131]
	s_mov_b32 m0, s40
	s_nop 0
	global_load_lds_dwordx4 v[224:225], off
	s_mov_b32 m0, s41
	s_nop 0
	global_load_lds_dwordx4 v[226:227], off
	s_cmp_eq_u32 s64, 0
	s_cbranch_scc1 .Lw8_11
	s_waitcnt vmcnt(24)
	s_branch .Lwe_11

.Lwe_11:
	s_waitcnt lgkmcnt(0)
	s_barrier
	s_nop 0
	s_waitcnt lgkmcnt(0)
	v_mfma_f32_16x16x32_bf16 v[62:65], v[156:159], v[188:191], v[62:65]
	v_mfma_f32_16x16x32_bf16 v[58:61], v[164:167], v[188:191], v[58:61]
	v_mfma_f32_16x16x32_bf16 v[54:57], v[156:159], v[196:199], v[54:57]
	v_mfma_f32_16x16x32_bf16 v[46:49], v[164:167], v[196:199], v[46:49]
	v_mfma_f32_16x16x32_bf16 v[38:41], v[156:159], v[204:207], v[38:41]
	v_mfma_f32_16x16x32_bf16 v[30:33], v[164:167], v[204:207], v[30:33]
	v_mfma_f32_16x16x32_bf16 v[22:25], v[156:159], v[212:215], v[22:25]
	v_mfma_f32_16x16x32_bf16 v[14:17], v[164:167], v[212:215], v[14:17]
	v_mfma_f32_16x16x32_bf16 v[62:65], v[160:163], v[192:195], v[62:65]
	v_mfma_f32_16x16x32_bf16 v[58:61], v[168:171], v[192:195], v[58:61]
	v_mfma_f32_16x16x32_bf16 v[54:57], v[160:163], v[200:203], v[54:57]
	v_mfma_f32_16x16x32_bf16 v[46:49], v[168:171], v[200:203], v[46:49]
	v_mfma_f32_16x16x32_bf16 v[38:41], v[160:163], v[208:211], v[38:41]
	v_mfma_f32_16x16x32_bf16 v[30:33], v[168:171], v[208:211], v[30:33]
	v_mfma_f32_16x16x32_bf16 v[22:25], v[160:163], v[216:219], v[22:25]
	v_mfma_f32_16x16x32_bf16 v[14:17], v[168:171], v[216:219], v[14:17]
	s_nop 0
	s_nop 0
	v_mfma_f32_16x16x32_bf16 v[50:53], v[172:175], v[188:191], v[50:53]
	v_mfma_f32_16x16x32_bf16 v[42:45], v[180:183], v[188:191], v[42:45]
	v_mfma_f32_16x16x32_bf16 v[34:37], v[172:175], v[196:199], v[34:37]
	v_mfma_f32_16x16x32_bf16 v[26:29], v[180:183], v[196:199], v[26:29]
	v_mfma_f32_16x16x32_bf16 v[18:21], v[172:175], v[204:207], v[18:21]
	v_mfma_f32_16x16x32_bf16 v[10:13], v[180:183], v[204:207], v[10:13]
	v_mfma_f32_16x16x32_bf16 v[6:9], v[172:175], v[212:215], v[6:9]
	v_mfma_f32_16x16x32_bf16 v[2:5], v[180:183], v[212:215], v[2:5]
	v_mfma_f32_16x16x32_bf16 v[50:53], v[176:179], v[192:195], v[50:53]
	v_mfma_f32_16x16x32_bf16 v[42:45], v[184:187], v[192:195], v[42:45]
	v_mfma_f32_16x16x32_bf16 v[34:37], v[176:179], v[200:203], v[34:37]
	v_mfma_f32_16x16x32_bf16 v[26:29], v[184:187], v[200:203], v[26:29]
	v_mfma_f32_16x16x32_bf16 v[18:21], v[176:179], v[208:211], v[18:21]
	v_mfma_f32_16x16x32_bf16 v[10:13], v[184:187], v[208:211], v[10:13]
	v_mfma_f32_16x16x32_bf16 v[6:9], v[176:179], v[216:219], v[6:9]
	v_mfma_f32_16x16x32_bf16 v[2:5], v[184:187], v[216:219], v[2:5]
	s_nop 0
	s_barrier
	s_add_i32 s62, 0, 0x18000
	s_add_i32 s63, 0, 0x1c000
	v_add_u32_e32 v168, s62, v150
	v_add_u32_e32 v184, s63, v150
	ds_read_b128 v[156:159], v168
	ds_read_b128 v[160:163], v168 offset:1024
	ds_read_b128 v[164:167], v168 offset:2048
	ds_read_b128 v[168:171], v168 offset:3072
	ds_read_b128 v[172:175], v184
	ds_read_b128 v[176:179], v184 offset:1024
	ds_read_b128 v[180:183], v184 offset:2048
	ds_read_b128 v[184:187], v184 offset:3072
	s_add_u32 s30, s30, 0x160000
	s_addc_u32 s31, s31, 0
	s_mov_b32 m0, s42
	v_lshl_add_u64 v[228:229], s[30:31], 0, v[130:131]
	ds_read_b128 v[188:191], v155 offset:32768
	ds_read_b128 v[192:195], v155 offset:33792
	ds_read_b128 v[196:199], v155 offset:34816
	ds_read_b128 v[200:203], v155 offset:35840
	ds_read_b128 v[204:207], v155 offset:36864
	ds_read_b128 v[208:211], v155 offset:37888
	ds_read_b128 v[212:215], v155 offset:38912
	ds_read_b128 v[216:219], v155 offset:39936
	global_load_lds_dwordx4 v[228:229], off
	v_lshl_add_u64 v[228:229], s[30:31], 0, v[134:135]
	s_mov_b32 m0, s43
	s_nop 0
	global_load_lds_dwordx4 v[228:229], off
	s_waitcnt vmcnt(8)
	s_waitcnt lgkmcnt(0)
	s_barrier
	s_nop 0
	s_waitcnt lgkmcnt(0)
	v_mfma_f32_16x16x32_bf16 v[126:129], v[156:159], v[188:191], v[126:129]
	v_mfma_f32_16x16x32_bf16 v[122:125], v[164:167], v[188:191], v[122:125]
	v_mfma_f32_16x16x32_bf16 v[118:121], v[156:159], v[196:199], v[118:121]
	v_mfma_f32_16x16x32_bf16 v[110:113], v[164:167], v[196:199], v[110:113]
	v_mfma_f32_16x16x32_bf16 v[102:105], v[156:159], v[204:207], v[102:105]
	v_mfma_f32_16x16x32_bf16 v[94:97], v[164:167], v[204:207], v[94:97]
	v_mfma_f32_16x16x32_bf16 v[86:89], v[156:159], v[212:215], v[86:89]
	v_mfma_f32_16x16x32_bf16 v[78:81], v[164:167], v[212:215], v[78:81]
	v_mfma_f32_16x16x32_bf16 v[126:129], v[160:163], v[192:195], v[126:129]
	v_mfma_f32_16x16x32_bf16 v[122:125], v[168:171], v[192:195], v[122:125]
	v_mfma_f32_16x16x32_bf16 v[118:121], v[160:163], v[200:203], v[118:121]
	v_mfma_f32_16x16x32_bf16 v[110:113], v[168:171], v[200:203], v[110:113]
	v_mfma_f32_16x16x32_bf16 v[102:105], v[160:163], v[208:211], v[102:105]
	v_mfma_f32_16x16x32_bf16 v[94:97], v[168:171], v[208:211], v[94:97]
	v_mfma_f32_16x16x32_bf16 v[86:89], v[160:163], v[216:219], v[86:89]
	v_mfma_f32_16x16x32_bf16 v[78:81], v[168:171], v[216:219], v[78:81]
	s_nop 0
	s_nop 0
	v_mfma_f32_16x16x32_bf16 v[114:117], v[172:175], v[188:191], v[114:117]
	v_mfma_f32_16x16x32_bf16 v[106:109], v[180:183], v[188:191], v[106:109]
	v_mfma_f32_16x16x32_bf16 v[98:101], v[172:175], v[196:199], v[98:101]
	v_mfma_f32_16x16x32_bf16 v[90:93], v[180:183], v[196:199], v[90:93]
	v_mfma_f32_16x16x32_bf16 v[82:85], v[172:175], v[204:207], v[82:85]
	v_mfma_f32_16x16x32_bf16 v[74:77], v[180:183], v[204:207], v[74:77]
	v_mfma_f32_16x16x32_bf16 v[70:73], v[172:175], v[212:215], v[70:73]
	v_mfma_f32_16x16x32_bf16 v[66:69], v[180:183], v[212:215], v[66:69]
	v_mfma_f32_16x16x32_bf16 v[114:117], v[176:179], v[192:195], v[114:117]
	v_mfma_f32_16x16x32_bf16 v[106:109], v[184:187], v[192:195], v[106:109]
	v_mfma_f32_16x16x32_bf16 v[98:101], v[176:179], v[200:203], v[98:101]
	v_mfma_f32_16x16x32_bf16 v[90:93], v[184:187], v[200:203], v[90:93]
	v_mfma_f32_16x16x32_bf16 v[82:85], v[176:179], v[208:211], v[82:85]
	v_mfma_f32_16x16x32_bf16 v[74:77], v[184:187], v[208:211], v[74:77]
	v_mfma_f32_16x16x32_bf16 v[70:73], v[176:179], v[216:219], v[70:73]
	v_mfma_f32_16x16x32_bf16 v[66:69], v[184:187], v[216:219], v[66:69]
	s_nop 0
	s_barrier
	s_add_i32 s30, s62, s39
	v_lshl_add_u64 v[220:221], v[220:221], 0, s[8:9]
	s_mov_b32 m0, s30
	ds_read_b128 v[188:191], v155 offset:49152
	ds_read_b128 v[192:195], v155 offset:50176
	ds_read_b128 v[196:199], v155 offset:51200
	ds_read_b128 v[200:203], v155 offset:52224
	ds_read_b128 v[204:207], v155 offset:53248
	ds_read_b128 v[208:211], v155 offset:54272
	ds_read_b128 v[212:215], v155 offset:55296
	ds_read_b128 v[216:219], v155 offset:56320
	global_load_lds_dwordx4 v[220:221], off
	s_add_i32 m0, s30, 0x2000
	s_add_u32 s28, s28, 0x160080
	v_lshl_add_u64 v[220:221], v[222:223], 0, s[8:9]
	s_addc_u32 s29, s29, 0
	s_add_i32 s30, s63, s39
	global_load_lds_dwordx4 v[220:221], off
	v_lshl_add_u64 v[220:221], s[28:29], 0, v[132:133]
	s_mov_b32 m0, s30
	s_nop 0
	global_load_lds_dwordx4 v[220:221], off
	v_lshl_add_u64 v[220:221], s[28:29], 0, v[136:137]
	s_add_i32 m0, s30, 0x2000
	s_nop 0
	global_load_lds_dwordx4 v[220:221], off
	v_lshl_add_u64 v[220:221], v[224:225], 0, s[8:9]
	s_mov_b32 m0, s44
	s_nop 0
	global_load_lds_dwordx4 v[220:221], off
	v_lshl_add_u64 v[220:221], v[226:227], 0, s[8:9]
	s_mov_b32 m0, s45
	s_nop 0
	global_load_lds_dwordx4 v[220:221], off
	s_waitcnt vmcnt(8)
	s_waitcnt lgkmcnt(0)
	s_barrier
	s_nop 0
	s_waitcnt lgkmcnt(0)
	v_mfma_f32_16x16x32_bf16 v[62:65], v[156:159], v[188:191], v[62:65]
	v_mfma_f32_16x16x32_bf16 v[58:61], v[164:167], v[188:191], v[58:61]
	v_mfma_f32_16x16x32_bf16 v[54:57], v[156:159], v[196:199], v[54:57]
	v_mfma_f32_16x16x32_bf16 v[46:49], v[164:167], v[196:199], v[46:49]
	v_mfma_f32_16x16x32_bf16 v[38:41], v[156:159], v[204:207], v[38:41]
	v_mfma_f32_16x16x32_bf16 v[30:33], v[164:167], v[204:207], v[30:33]
	v_mfma_f32_16x16x32_bf16 v[22:25], v[156:159], v[212:215], v[22:25]
	v_mfma_f32_16x16x32_bf16 v[14:17], v[164:167], v[212:215], v[14:17]
	v_mfma_f32_16x16x32_bf16 v[62:65], v[160:163], v[192:195], v[62:65]
	v_mfma_f32_16x16x32_bf16 v[58:61], v[168:171], v[192:195], v[58:61]
	v_mfma_f32_16x16x32_bf16 v[54:57], v[160:163], v[200:203], v[54:57]
	v_mfma_f32_16x16x32_bf16 v[46:49], v[168:171], v[200:203], v[46:49]
	v_mfma_f32_16x16x32_bf16 v[38:41], v[160:163], v[208:211], v[38:41]
	v_mfma_f32_16x16x32_bf16 v[30:33], v[168:171], v[208:211], v[30:33]
	v_mfma_f32_16x16x32_bf16 v[22:25], v[160:163], v[216:219], v[22:25]
	v_mfma_f32_16x16x32_bf16 v[14:17], v[168:171], v[216:219], v[14:17]
	s_nop 0
	s_nop 0
	v_mfma_f32_16x16x32_bf16 v[50:53], v[172:175], v[188:191], v[50:53]
	v_mfma_f32_16x16x32_bf16 v[42:45], v[180:183], v[188:191], v[42:45]
	v_mfma_f32_16x16x32_bf16 v[34:37], v[172:175], v[196:199], v[34:37]
	v_mfma_f32_16x16x32_bf16 v[26:29], v[180:183], v[196:199], v[26:29]
	v_mfma_f32_16x16x32_bf16 v[18:21], v[172:175], v[204:207], v[18:21]
	v_mfma_f32_16x16x32_bf16 v[10:13], v[180:183], v[204:207], v[10:13]
	v_mfma_f32_16x16x32_bf16 v[6:9], v[172:175], v[212:215], v[6:9]
	v_mfma_f32_16x16x32_bf16 v[2:5], v[180:183], v[212:215], v[2:5]
	v_mfma_f32_16x16x32_bf16 v[50:53], v[176:179], v[192:195], v[50:53]
	v_mfma_f32_16x16x32_bf16 v[42:45], v[184:187], v[192:195], v[42:45]
	v_mfma_f32_16x16x32_bf16 v[34:37], v[176:179], v[200:203], v[34:37]
	v_mfma_f32_16x16x32_bf16 v[26:29], v[184:187], v[200:203], v[26:29]
	v_mfma_f32_16x16x32_bf16 v[18:21], v[176:179], v[208:211], v[18:21]
	v_mfma_f32_16x16x32_bf16 v[10:13], v[184:187], v[208:211], v[10:13]
	v_mfma_f32_16x16x32_bf16 v[6:9], v[176:179], v[216:219], v[6:9]
	v_mfma_f32_16x16x32_bf16 v[2:5], v[184:187], v[216:219], v[2:5]
	s_nop 0
	s_barrier
	s_add_i32 s61, s61, 2
	s_add_u32 s26, s26, 0x100
	s_addc_u32 s27, s27, 0
	s_cmpk_gt_u32 s61, 0x55
	s_cbranch_scc0 .LBB0_1417
	s_setprio 0
	s_and_b64 vcc, exec, s[10:11]
	s_cbranch_vccz .LBB0_1420
	s_barrier

.LBB0_1586:
	s_xor_b64 s[34:35], s[0:1], -1
	s_cmp_lg_u32 s42, 0
	s_mov_b64 s[0:1], s[36:37]
	s_cselect_b64 s[36:37], -1, 0
	s_add_u32 s25, s38, 0x100
	v_mov_b32_e32 v2, 0
	s_addc_u32 s27, s39, 0
	v_lshl_add_u64 v[146:147], s[30:31], 0, v[138:139]
	v_lshl_add_u64 v[148:149], s[30:31], 0, v[140:141]
	s_mov_b32 s69, -2
	s_mov_b64 s[38:39], 0
	v_mov_b32_e32 v3, v2
	v_mov_b32_e32 v4, v2
	v_mov_b32_e32 v5, v2
	v_mov_b32_e32 v6, v2
	v_mov_b32_e32 v7, v2
	v_mov_b32_e32 v8, v2
	v_mov_b32_e32 v9, v2
	v_mov_b32_e32 v10, v2
	v_mov_b32_e32 v11, v2
	v_mov_b32_e32 v12, v2
	v_mov_b32_e32 v13, v2
	v_mov_b32_e32 v18, v2
	v_mov_b32_e32 v19, v2
	v_mov_b32_e32 v20, v2
	v_mov_b32_e32 v21, v2
	v_mov_b32_e32 v26, v2
	v_mov_b32_e32 v27, v2
	v_mov_b32_e32 v28, v2
	v_mov_b32_e32 v29, v2
	v_mov_b32_e32 v34, v2
	v_mov_b32_e32 v35, v2
	v_mov_b32_e32 v36, v2
	v_mov_b32_e32 v37, v2
	v_mov_b32_e32 v42, v2
	v_mov_b32_e32 v43, v2
	v_mov_b32_e32 v44, v2
	v_mov_b32_e32 v45, v2
	v_mov_b32_e32 v50, v2
	v_mov_b32_e32 v51, v2
	v_mov_b32_e32 v52, v2
	v_mov_b32_e32 v53, v2
	v_mov_b32_e32 v14, v2
	v_mov_b32_e32 v15, v2
	v_mov_b32_e32 v16, v2
	v_mov_b32_e32 v17, v2
	v_mov_b32_e32 v22, v2
	v_mov_b32_e32 v23, v2
	v_mov_b32_e32 v24, v2
	v_mov_b32_e32 v25, v2
	v_mov_b32_e32 v30, v2
	v_mov_b32_e32 v31, v2
	v_mov_b32_e32 v32, v2
	v_mov_b32_e32 v33, v2
	v_mov_b32_e32 v38, v2
	v_mov_b32_e32 v39, v2
	v_mov_b32_e32 v40, v2
	v_mov_b32_e32 v41, v2
	v_mov_b32_e32 v46, v2
	v_mov_b32_e32 v47, v2
	v_mov_b32_e32 v48, v2
	v_mov_b32_e32 v49, v2
	v_mov_b32_e32 v54, v2
	v_mov_b32_e32 v55, v2
	v_mov_b32_e32 v56, v2
	v_mov_b32_e32 v57, v2
	v_mov_b32_e32 v58, v2
	v_mov_b32_e32 v59, v2
	v_mov_b32_e32 v60, v2
	v_mov_b32_e32 v61, v2
	v_mov_b32_e32 v62, v2
	v_mov_b32_e32 v63, v2
	v_mov_b32_e32 v64, v2
	v_mov_b32_e32 v65, v2
	v_mov_b32_e32 v66, v2
	v_mov_b32_e32 v67, v2
	v_mov_b32_e32 v68, v2
	v_mov_b32_e32 v69, v2
	v_mov_b32_e32 v70, v2
	v_mov_b32_e32 v71, v2
	v_mov_b32_e32 v72, v2
	v_mov_b32_e32 v73, v2
	v_mov_b32_e32 v74, v2
	v_mov_b32_e32 v75, v2
	v_mov_b32_e32 v76, v2
	v_mov_b32_e32 v77, v2
	v_mov_b32_e32 v82, v2
	v_mov_b32_e32 v83, v2
	v_mov_b32_e32 v84, v2
	v_mov_b32_e32 v85, v2
	v_mov_b32_e32 v90, v2
	v_mov_b32_e32 v91, v2
	v_mov_b32_e32 v92, v2
	v_mov_b32_e32 v93, v2
	v_mov_b32_e32 v98, v2
	v_mov_b32_e32 v99, v2
	v_mov_b32_e32 v100, v2
	v_mov_b32_e32 v101, v2
	v_mov_b32_e32 v106, v2
	v_mov_b32_e32 v107, v2
	v_mov_b32_e32 v108, v2
	v_mov_b32_e32 v109, v2
	v_mov_b32_e32 v114, v2
	v_mov_b32_e32 v115, v2
	v_mov_b32_e32 v116, v2
	v_mov_b32_e32 v117, v2
	v_mov_b32_e32 v78, v2
	v_mov_b32_e32 v79, v2
	v_mov_b32_e32 v80, v2
	v_mov_b32_e32 v81, v2
	v_mov_b32_e32 v86, v2
	v_mov_b32_e32 v87, v2
	v_mov_b32_e32 v88, v2
	v_mov_b32_e32 v89, v2
	v_mov_b32_e32 v94, v2
	v_mov_b32_e32 v95, v2
	v_mov_b32_e32 v96, v2
	v_mov_b32_e32 v97, v2
	v_mov_b32_e32 v102, v2
	v_mov_b32_e32 v103, v2
	v_mov_b32_e32 v104, v2
	v_mov_b32_e32 v105, v2
	v_mov_b32_e32 v110, v2
	v_mov_b32_e32 v111, v2
	v_mov_b32_e32 v112, v2
	v_mov_b32_e32 v113, v2
	v_mov_b32_e32 v118, v2
	v_mov_b32_e32 v119, v2
	v_mov_b32_e32 v120, v2
	v_mov_b32_e32 v121, v2
	v_mov_b32_e32 v122, v2
	v_mov_b32_e32 v123, v2
	v_mov_b32_e32 v124, v2
	v_mov_b32_e32 v125, v2
	v_mov_b32_e32 v126, v2
	v_mov_b32_e32 v127, v2
	v_mov_b32_e32 v128, v2
	v_mov_b32_e32 v129, v2
	v_readfirstlane_b32 s98, v154
	s_lshr_b32 s98, s98, 8
	s_cmp_eq_u32 s98, 0
	s_cbranch_scc1 .Lgprio_6
	s_setprio 1
.Lgprio_6:
.LBB0_1587:
	ds_read_b128 v[158:161], v153
	ds_read_b128 v[162:165], v153 offset:1024
	ds_read_b128 v[166:169], v153 offset:2048
	ds_read_b128 v[170:173], v153 offset:3072
	ds_read_b128 v[174:177], v155
	ds_read_b128 v[178:181], v155 offset:1024
	ds_read_b128 v[182:185], v155 offset:2048
	ds_read_b128 v[186:189], v155 offset:3072
	s_add_u32 s40, s30, s38
	s_addc_u32 s41, s31, s39
	s_add_u32 s42, s40, 0x100
	s_addc_u32 s43, s41, 0
	s_add_u32 s70, s25, s38
	s_addc_u32 s71, s27, s39
	s_cmp_eq_u32 s38, 0
	s_cselect_b64 s[40:41], -1, 0
	s_and_b64 s[40:41], s[36:37], s[40:41]
	s_cmpk_eq_i32 s38, 0xf00
	v_cndmask_b32_e64 v157, 0, 1, s[40:41]
	s_cselect_b32 s43, s7, s43
	s_cselect_b32 s42, s6, s42
	v_readfirstlane_b32 s72, v157
	s_cselect_b32 s41, s29, s71
	s_cselect_b32 s40, s28, s70
	v_lshl_add_u64 v[222:223], v[148:149], 0, s[38:39]
	s_add_i32 m0, s51, 0xc000
	ds_read_b128 v[190:193], v156
	ds_read_b128 v[194:197], v156 offset:1024
	ds_read_b128 v[198:201], v156 offset:2048
	ds_read_b128 v[202:205], v156 offset:3072
	ds_read_b128 v[206:209], v156 offset:4096
	ds_read_b128 v[210:213], v156 offset:5120
	ds_read_b128 v[214:217], v156 offset:6144
	ds_read_b128 v[218:221], v156 offset:7168
	global_load_lds_dwordx4 v[222:223], off
	v_lshl_add_u64 v[222:223], v[146:147], 0, s[38:39]
	s_add_i32 m0, s51, 0xe000
	s_and_b32 s72, s72, 1
	global_load_lds_dwordx4 v[222:223], off
	s_cmp_eq_u32 s72, 0
	s_cbranch_scc1 .Lw8_12
	s_waitcnt vmcnt(24)
	s_branch .Lwe_12

.Lwe_12:
	s_waitcnt lgkmcnt(0)
	s_barrier
	s_nop 0
	s_waitcnt lgkmcnt(0)
	v_mfma_f32_16x16x32_bf16 v[126:129], v[158:161], v[190:193], v[126:129]
	v_mfma_f32_16x16x32_bf16 v[122:125], v[166:169], v[190:193], v[122:125]
	v_mfma_f32_16x16x32_bf16 v[118:121], v[158:161], v[198:201], v[118:121]
	v_mfma_f32_16x16x32_bf16 v[110:113], v[166:169], v[198:201], v[110:113]
	v_mfma_f32_16x16x32_bf16 v[102:105], v[158:161], v[206:209], v[102:105]
	v_mfma_f32_16x16x32_bf16 v[94:97], v[166:169], v[206:209], v[94:97]
	v_mfma_f32_16x16x32_bf16 v[86:89], v[158:161], v[214:217], v[86:89]
	v_mfma_f32_16x16x32_bf16 v[78:81], v[166:169], v[214:217], v[78:81]
	v_mfma_f32_16x16x32_bf16 v[126:129], v[162:165], v[194:197], v[126:129]
	v_mfma_f32_16x16x32_bf16 v[122:125], v[170:173], v[194:197], v[122:125]
	v_mfma_f32_16x16x32_bf16 v[118:121], v[162:165], v[202:205], v[118:121]
	v_mfma_f32_16x16x32_bf16 v[110:113], v[170:173], v[202:205], v[110:113]
	v_mfma_f32_16x16x32_bf16 v[102:105], v[162:165], v[210:213], v[102:105]
	v_mfma_f32_16x16x32_bf16 v[94:97], v[170:173], v[210:213], v[94:97]
	v_mfma_f32_16x16x32_bf16 v[86:89], v[162:165], v[218:221], v[86:89]
	v_mfma_f32_16x16x32_bf16 v[78:81], v[170:173], v[218:221], v[78:81]
	s_nop 0
	s_nop 0
	v_mfma_f32_16x16x32_bf16 v[114:117], v[174:177], v[190:193], v[114:117]
	v_mfma_f32_16x16x32_bf16 v[106:109], v[182:185], v[190:193], v[106:109]
	v_mfma_f32_16x16x32_bf16 v[98:101], v[174:177], v[198:201], v[98:101]
	v_mfma_f32_16x16x32_bf16 v[90:93], v[182:185], v[198:201], v[90:93]
	v_mfma_f32_16x16x32_bf16 v[82:85], v[174:177], v[206:209], v[82:85]
	v_mfma_f32_16x16x32_bf16 v[74:77], v[182:185], v[206:209], v[74:77]
	v_mfma_f32_16x16x32_bf16 v[70:73], v[174:177], v[214:217], v[70:73]
	v_mfma_f32_16x16x32_bf16 v[66:69], v[182:185], v[214:217], v[66:69]
	v_mfma_f32_16x16x32_bf16 v[114:117], v[178:181], v[194:197], v[114:117]
	v_mfma_f32_16x16x32_bf16 v[106:109], v[186:189], v[194:197], v[106:109]
	v_mfma_f32_16x16x32_bf16 v[98:101], v[178:181], v[202:205], v[98:101]
	v_mfma_f32_16x16x32_bf16 v[90:93], v[186:189], v[202:205], v[90:93]
	v_mfma_f32_16x16x32_bf16 v[82:85], v[178:181], v[210:213], v[82:85]
	v_mfma_f32_16x16x32_bf16 v[74:77], v[186:189], v[210:213], v[74:77]
	v_mfma_f32_16x16x32_bf16 v[70:73], v[178:181], v[218:221], v[70:73]
	v_mfma_f32_16x16x32_bf16 v[66:69], v[186:189], v[218:221], v[66:69]
	s_nop 0
	s_barrier
	s_add_i32 s70, s60, s48
	v_lshl_add_u64 v[222:223], s[40:41], 0, v[134:135]
	s_mov_b32 m0, s70
	ds_read_b128 v[190:193], v156 offset:16384
	ds_read_b128 v[194:197], v156 offset:17408
	ds_read_b128 v[198:201], v156 offset:18432
	ds_read_b128 v[202:205], v156 offset:19456
	ds_read_b128 v[206:209], v156 offset:20480
	ds_read_b128 v[210:213], v156 offset:21504
	ds_read_b128 v[214:217], v156 offset:22528
	ds_read_b128 v[218:221], v156 offset:23552
	global_load_lds_dwordx4 v[222:223], off
	s_add_i32 m0, s70, 0x2000
	s_add_u32 s70, s40, 0x80000
	v_lshl_add_u64 v[224:225], s[40:41], 0, v[130:131]
	s_addc_u32 s71, s41, 0
	s_add_i32 s73, s61, s48
	global_load_lds_dwordx4 v[224:225], off
	v_lshl_add_u64 v[226:227], s[70:71], 0, v[134:135]
	s_mov_b32 m0, s73
	v_lshl_add_u64 v[228:229], s[42:43], 0, v[132:133]
	global_load_lds_dwordx4 v[226:227], off
	v_lshl_add_u64 v[226:227], s[70:71], 0, v[130:131]
	s_add_i32 m0, s73, 0x2000
	s_nop 0
	global_load_lds_dwordx4 v[226:227], off
	v_lshl_add_u64 v[226:227], s[42:43], 0, v[136:137]
	s_mov_b32 m0, s51
	s_nop 0
	global_load_lds_dwordx4 v[226:227], off
	s_mov_b32 m0, s52
	s_nop 0
	global_load_lds_dwordx4 v[228:229], off
	s_cmp_eq_u32 s72, 0
	s_cbranch_scc1 .Lw8_13
	s_waitcnt vmcnt(24)
	s_branch .Lwe_13

.Lwe_13:
	s_waitcnt lgkmcnt(0)
	s_barrier
	s_nop 0
	s_waitcnt lgkmcnt(0)
	v_mfma_f32_16x16x32_bf16 v[62:65], v[158:161], v[190:193], v[62:65]
	v_mfma_f32_16x16x32_bf16 v[58:61], v[166:169], v[190:193], v[58:61]
	v_mfma_f32_16x16x32_bf16 v[54:57], v[158:161], v[198:201], v[54:57]
	v_mfma_f32_16x16x32_bf16 v[46:49], v[166:169], v[198:201], v[46:49]
	v_mfma_f32_16x16x32_bf16 v[38:41], v[158:161], v[206:209], v[38:41]
	v_mfma_f32_16x16x32_bf16 v[30:33], v[166:169], v[206:209], v[30:33]
	v_mfma_f32_16x16x32_bf16 v[22:25], v[158:161], v[214:217], v[22:25]
	v_mfma_f32_16x16x32_bf16 v[14:17], v[166:169], v[214:217], v[14:17]
	v_mfma_f32_16x16x32_bf16 v[62:65], v[162:165], v[194:197], v[62:65]
	v_mfma_f32_16x16x32_bf16 v[58:61], v[170:173], v[194:197], v[58:61]
	v_mfma_f32_16x16x32_bf16 v[54:57], v[162:165], v[202:205], v[54:57]
	v_mfma_f32_16x16x32_bf16 v[46:49], v[170:173], v[202:205], v[46:49]
	v_mfma_f32_16x16x32_bf16 v[38:41], v[162:165], v[210:213], v[38:41]
	v_mfma_f32_16x16x32_bf16 v[30:33], v[170:173], v[210:213], v[30:33]
	v_mfma_f32_16x16x32_bf16 v[22:25], v[162:165], v[218:221], v[22:25]
	v_mfma_f32_16x16x32_bf16 v[14:17], v[170:173], v[218:221], v[14:17]
	s_nop 0
	s_nop 0
	v_mfma_f32_16x16x32_bf16 v[50:53], v[174:177], v[190:193], v[50:53]
	v_mfma_f32_16x16x32_bf16 v[42:45], v[182:185], v[190:193], v[42:45]
	v_mfma_f32_16x16x32_bf16 v[34:37], v[174:177], v[198:201], v[34:37]
	v_mfma_f32_16x16x32_bf16 v[26:29], v[182:185], v[198:201], v[26:29]
	v_mfma_f32_16x16x32_bf16 v[18:21], v[174:177], v[206:209], v[18:21]
	v_mfma_f32_16x16x32_bf16 v[10:13], v[182:185], v[206:209], v[10:13]
	v_mfma_f32_16x16x32_bf16 v[6:9], v[174:177], v[214:217], v[6:9]
	v_mfma_f32_16x16x32_bf16 v[2:5], v[182:185], v[214:217], v[2:5]
	v_mfma_f32_16x16x32_bf16 v[50:53], v[178:181], v[194:197], v[50:53]
	v_mfma_f32_16x16x32_bf16 v[42:45], v[186:189], v[194:197], v[42:45]
	v_mfma_f32_16x16x32_bf16 v[34:37], v[178:181], v[202:205], v[34:37]
	v_mfma_f32_16x16x32_bf16 v[26:29], v[186:189], v[202:205], v[26:29]
	v_mfma_f32_16x16x32_bf16 v[18:21], v[178:181], v[210:213], v[18:21]
	v_mfma_f32_16x16x32_bf16 v[10:13], v[186:189], v[210:213], v[10:13]
	v_mfma_f32_16x16x32_bf16 v[6:9], v[178:181], v[218:221], v[6:9]
	v_mfma_f32_16x16x32_bf16 v[2:5], v[186:189], v[218:221], v[2:5]
	s_nop 0
	s_barrier
	s_add_i32 s70, 0, 0x18000
	v_add_u32_e32 v157, s70, v150
	s_add_i32 s71, 0, 0x1c000
	ds_read_b128 v[158:161], v157
	ds_read_b128 v[162:165], v157 offset:1024
	ds_read_b128 v[166:169], v157 offset:2048
	ds_read_b128 v[170:173], v157 offset:3072
	v_add_u32_e32 v157, s71, v150
	ds_read_b128 v[174:177], v157
	ds_read_b128 v[178:181], v157 offset:1024
	ds_read_b128 v[182:185], v157 offset:2048
	ds_read_b128 v[186:189], v157 offset:3072
	s_add_u32 s42, s42, 0x80000
	s_addc_u32 s43, s43, 0
	s_mov_b32 m0, s53
	v_lshl_add_u64 v[230:231], s[42:43], 0, v[136:137]
	ds_read_b128 v[190:193], v156 offset:32768
	ds_read_b128 v[194:197], v156 offset:33792
	ds_read_b128 v[198:201], v156 offset:34816
	ds_read_b128 v[202:205], v156 offset:35840
	ds_read_b128 v[206:209], v156 offset:36864
	ds_read_b128 v[210:213], v156 offset:37888
	ds_read_b128 v[214:217], v156 offset:38912
	ds_read_b128 v[218:221], v156 offset:39936
	global_load_lds_dwordx4 v[230:231], off
	v_lshl_add_u64 v[230:231], s[42:43], 0, v[132:133]
	s_mov_b32 m0, s54
	s_nop 0
	global_load_lds_dwordx4 v[230:231], off
	s_waitcnt vmcnt(8)
	s_waitcnt lgkmcnt(0)
	s_barrier
	s_nop 0
	s_waitcnt lgkmcnt(0)
	v_mfma_f32_16x16x32_bf16 v[126:129], v[158:161], v[190:193], v[126:129]
	v_mfma_f32_16x16x32_bf16 v[122:125], v[166:169], v[190:193], v[122:125]
	v_mfma_f32_16x16x32_bf16 v[118:121], v[158:161], v[198:201], v[118:121]
	v_mfma_f32_16x16x32_bf16 v[110:113], v[166:169], v[198:201], v[110:113]
	v_mfma_f32_16x16x32_bf16 v[102:105], v[158:161], v[206:209], v[102:105]
	v_mfma_f32_16x16x32_bf16 v[94:97], v[166:169], v[206:209], v[94:97]
	v_mfma_f32_16x16x32_bf16 v[86:89], v[158:161], v[214:217], v[86:89]
	v_mfma_f32_16x16x32_bf16 v[78:81], v[166:169], v[214:217], v[78:81]
	v_mfma_f32_16x16x32_bf16 v[126:129], v[162:165], v[194:197], v[126:129]
	v_mfma_f32_16x16x32_bf16 v[122:125], v[170:173], v[194:197], v[122:125]
	v_mfma_f32_16x16x32_bf16 v[118:121], v[162:165], v[202:205], v[118:121]
	v_mfma_f32_16x16x32_bf16 v[110:113], v[170:173], v[202:205], v[110:113]
	v_mfma_f32_16x16x32_bf16 v[102:105], v[162:165], v[210:213], v[102:105]
	v_mfma_f32_16x16x32_bf16 v[94:97], v[170:173], v[210:213], v[94:97]
	v_mfma_f32_16x16x32_bf16 v[86:89], v[162:165], v[218:221], v[86:89]
	v_mfma_f32_16x16x32_bf16 v[78:81], v[170:173], v[218:221], v[78:81]
	s_nop 0
	s_nop 0
	v_mfma_f32_16x16x32_bf16 v[114:117], v[174:177], v[190:193], v[114:117]
	v_mfma_f32_16x16x32_bf16 v[106:109], v[182:185], v[190:193], v[106:109]
	v_mfma_f32_16x16x32_bf16 v[98:101], v[174:177], v[198:201], v[98:101]
	v_mfma_f32_16x16x32_bf16 v[90:93], v[182:185], v[198:201], v[90:93]
	v_mfma_f32_16x16x32_bf16 v[82:85], v[174:177], v[206:209], v[82:85]
	v_mfma_f32_16x16x32_bf16 v[74:77], v[182:185], v[206:209], v[74:77]
	v_mfma_f32_16x16x32_bf16 v[70:73], v[174:177], v[214:217], v[70:73]
	v_mfma_f32_16x16x32_bf16 v[66:69], v[182:185], v[214:217], v[66:69]
	v_mfma_f32_16x16x32_bf16 v[114:117], v[178:181], v[194:197], v[114:117]
	v_mfma_f32_16x16x32_bf16 v[106:109], v[186:189], v[194:197], v[106:109]
	v_mfma_f32_16x16x32_bf16 v[98:101], v[178:181], v[202:205], v[98:101]
	v_mfma_f32_16x16x32_bf16 v[90:93], v[186:189], v[202:205], v[90:93]
	v_mfma_f32_16x16x32_bf16 v[82:85], v[178:181], v[210:213], v[82:85]
	v_mfma_f32_16x16x32_bf16 v[74:77], v[186:189], v[210:213], v[74:77]
	v_mfma_f32_16x16x32_bf16 v[70:73], v[178:181], v[218:221], v[70:73]
	v_mfma_f32_16x16x32_bf16 v[66:69], v[186:189], v[218:221], v[66:69]
	s_nop 0
	s_barrier
	s_add_i32 s42, s70, s48
	v_lshl_add_u64 v[222:223], v[222:223], 0, s[12:13]
	s_mov_b32 m0, s42
	ds_read_b128 v[190:193], v156 offset:49152
	ds_read_b128 v[194:197], v156 offset:50176
	ds_read_b128 v[198:201], v156 offset:51200
	ds_read_b128 v[202:205], v156 offset:52224
	ds_read_b128 v[206:209], v156 offset:53248
	ds_read_b128 v[210:213], v156 offset:54272
	ds_read_b128 v[214:217], v156 offset:55296
	ds_read_b128 v[218:221], v156 offset:56320
	global_load_lds_dwordx4 v[222:223], off
	s_add_i32 m0, s42, 0x2000
	s_add_u32 s40, s40, 0x80080
	v_lshl_add_u64 v[222:223], v[224:225], 0, s[12:13]
	s_addc_u32 s41, s41, 0
	s_add_i32 s42, s71, s48
	global_load_lds_dwordx4 v[222:223], off
	v_lshl_add_u64 v[222:223], s[40:41], 0, v[134:135]
	s_mov_b32 m0, s42
	s_nop 0
	global_load_lds_dwordx4 v[222:223], off
	v_lshl_add_u64 v[222:223], s[40:41], 0, v[130:131]
	s_add_i32 m0, s42, 0x2000
	s_nop 0
	global_load_lds_dwordx4 v[222:223], off
	v_lshl_add_u64 v[222:223], v[226:227], 0, s[12:13]
	s_mov_b32 m0, s56
	s_nop 0
	global_load_lds_dwordx4 v[222:223], off
	v_lshl_add_u64 v[222:223], v[228:229], 0, s[12:13]
	s_mov_b32 m0, s57
	s_nop 0
	global_load_lds_dwordx4 v[222:223], off
	s_waitcnt vmcnt(8)
	s_waitcnt lgkmcnt(0)
	s_barrier
	s_nop 0
	s_waitcnt lgkmcnt(0)
	v_mfma_f32_16x16x32_bf16 v[62:65], v[158:161], v[190:193], v[62:65]
	v_mfma_f32_16x16x32_bf16 v[58:61], v[166:169], v[190:193], v[58:61]
	v_mfma_f32_16x16x32_bf16 v[54:57], v[158:161], v[198:201], v[54:57]
	v_mfma_f32_16x16x32_bf16 v[46:49], v[166:169], v[198:201], v[46:49]
	v_mfma_f32_16x16x32_bf16 v[38:41], v[158:161], v[206:209], v[38:41]
	v_mfma_f32_16x16x32_bf16 v[30:33], v[166:169], v[206:209], v[30:33]
	v_mfma_f32_16x16x32_bf16 v[22:25], v[158:161], v[214:217], v[22:25]
	v_mfma_f32_16x16x32_bf16 v[14:17], v[166:169], v[214:217], v[14:17]
	v_mfma_f32_16x16x32_bf16 v[62:65], v[162:165], v[194:197], v[62:65]
	v_mfma_f32_16x16x32_bf16 v[58:61], v[170:173], v[194:197], v[58:61]
	v_mfma_f32_16x16x32_bf16 v[54:57], v[162:165], v[202:205], v[54:57]
	v_mfma_f32_16x16x32_bf16 v[46:49], v[170:173], v[202:205], v[46:49]
	v_mfma_f32_16x16x32_bf16 v[38:41], v[162:165], v[210:213], v[38:41]
	v_mfma_f32_16x16x32_bf16 v[30:33], v[170:173], v[210:213], v[30:33]
	v_mfma_f32_16x16x32_bf16 v[22:25], v[162:165], v[218:221], v[22:25]
	v_mfma_f32_16x16x32_bf16 v[14:17], v[170:173], v[218:221], v[14:17]
	s_nop 0
	s_nop 0
	v_mfma_f32_16x16x32_bf16 v[50:53], v[174:177], v[190:193], v[50:53]
	v_mfma_f32_16x16x32_bf16 v[42:45], v[182:185], v[190:193], v[42:45]
	v_mfma_f32_16x16x32_bf16 v[34:37], v[174:177], v[198:201], v[34:37]
	v_mfma_f32_16x16x32_bf16 v[26:29], v[182:185], v[198:201], v[26:29]
	v_mfma_f32_16x16x32_bf16 v[18:21], v[174:177], v[206:209], v[18:21]
	v_mfma_f32_16x16x32_bf16 v[10:13], v[182:185], v[206:209], v[10:13]
	v_mfma_f32_16x16x32_bf16 v[6:9], v[174:177], v[214:217], v[6:9]
	v_mfma_f32_16x16x32_bf16 v[2:5], v[182:185], v[214:217], v[2:5]
	v_mfma_f32_16x16x32_bf16 v[50:53], v[178:181], v[194:197], v[50:53]
	v_mfma_f32_16x16x32_bf16 v[42:45], v[186:189], v[194:197], v[42:45]
	v_mfma_f32_16x16x32_bf16 v[34:37], v[178:181], v[202:205], v[34:37]
	v_mfma_f32_16x16x32_bf16 v[26:29], v[186:189], v[202:205], v[26:29]
	v_mfma_f32_16x16x32_bf16 v[18:21], v[178:181], v[210:213], v[18:21]
	v_mfma_f32_16x16x32_bf16 v[10:13], v[186:189], v[210:213], v[10:13]
	v_mfma_f32_16x16x32_bf16 v[6:9], v[178:181], v[218:221], v[6:9]
	v_mfma_f32_16x16x32_bf16 v[2:5], v[186:189], v[218:221], v[2:5]
	s_nop 0
	s_barrier
	s_add_i32 s69, s69, 2
	s_add_u32 s38, s38, 0x100
	s_addc_u32 s39, s39, 0
	s_cmp_gt_u32 s69, 29
	s_cbranch_scc0 .LBB0_1587
	s_setprio 0
	s_and_b64 vcc, exec, s[14:15]
	s_cbranch_vccnz .LBB0_1592
	s_mov_b64 s[30:31], -1
	s_and_b64 vcc, exec, s[34:35]
	s_cbranch_vccnz .LBB0_1593
